# hand-written EpiRes epilogues (P7, P9, P12: all base loads up front, 64-lane row-sum atomics) and 64-bit accumulator zeroing at unit start
# speedup vs baseline: 1.0483x; 1.0010x over previous
.LBB0_376:
	s_ashr_i32 s27, s26, 31
	s_lshl_b64 s[8:9], s[26:27], 19
	s_add_u32 s28, s94, s8
	s_addc_u32 s29, s95, s9
	s_and_b64 s[8:9], s[4:5], exec
	s_cselect_b32 s7, s29, s39
	s_cselect_b32 s12, s28, s38
	s_ashr_i32 s23, s22, 31
	s_lshl_b64 s[8:9], s[22:23], 19
	s_add_u32 s30, s96, s8
	s_addc_u32 s31, s97, s9
	s_and_b64 s[8:9], s[4:5], exec
	s_cselect_b32 s13, s31, s41
	s_cselect_b32 s23, s30, s40
	s_add_u32 s38, s38, 0x40080
	s_addc_u32 s39, s39, 0
	s_add_u32 s27, s40, 0x100
	v_mov_b32_e32 v0, 0
	s_addc_u32 s35, s41, 0
	s_mov_b32 s8, -2
	v_mov_b32_e32 v1, 0
	v_mov_b64_e32 v[2:3], 0
	v_mov_b64_e32 v[4:5], 0
	v_mov_b64_e32 v[6:7], 0
	v_mov_b64_e32 v[8:9], 0
	v_mov_b64_e32 v[10:11], 0
	v_mov_b64_e32 v[12:13], 0
	v_mov_b64_e32 v[14:15], 0
	v_mov_b64_e32 v[16:17], 0
	v_mov_b64_e32 v[18:19], 0
	v_mov_b64_e32 v[20:21], 0
	v_mov_b64_e32 v[22:23], 0
	v_mov_b64_e32 v[24:25], 0
	v_mov_b64_e32 v[26:27], 0
	v_mov_b64_e32 v[28:29], 0
	v_mov_b64_e32 v[30:31], 0
	v_mov_b64_e32 v[32:33], 0
	v_mov_b64_e32 v[34:35], 0
	v_mov_b64_e32 v[36:37], 0
	v_mov_b64_e32 v[38:39], 0
	v_mov_b64_e32 v[40:41], 0
	v_mov_b64_e32 v[42:43], 0
	v_mov_b64_e32 v[44:45], 0
	v_mov_b64_e32 v[46:47], 0
	v_mov_b64_e32 v[48:49], 0
	v_mov_b64_e32 v[50:51], 0
	v_mov_b64_e32 v[52:53], 0
	v_mov_b64_e32 v[54:55], 0
	v_mov_b64_e32 v[56:57], 0
	v_mov_b64_e32 v[58:59], 0
	v_mov_b64_e32 v[60:61], 0
	v_mov_b64_e32 v[62:63], 0
	v_mov_b64_e32 v[64:65], 0
	v_mov_b64_e32 v[66:67], 0
	v_mov_b64_e32 v[68:69], 0
	v_mov_b64_e32 v[70:71], 0
	v_mov_b64_e32 v[72:73], 0
	v_mov_b64_e32 v[74:75], 0
	v_mov_b64_e32 v[76:77], 0
	v_mov_b64_e32 v[78:79], 0
	v_mov_b64_e32 v[96:97], 0
	v_mov_b64_e32 v[98:99], 0
	v_mov_b64_e32 v[100:101], 0
	v_mov_b64_e32 v[102:103], 0
	v_mov_b64_e32 v[104:105], 0
	v_mov_b64_e32 v[106:107], 0
	v_mov_b64_e32 v[108:109], 0
	v_mov_b64_e32 v[110:111], 0
	v_mov_b64_e32 v[112:113], 0
	v_mov_b64_e32 v[114:115], 0
	v_mov_b64_e32 v[116:117], 0
	v_mov_b64_e32 v[118:119], 0
	v_mov_b64_e32 v[120:121], 0
	v_mov_b64_e32 v[122:123], 0
	v_mov_b64_e32 v[124:125], 0
	v_mov_b64_e32 v[126:127], 0
	v_mov_b64_e32 v[128:129], 0
	v_mov_b64_e32 v[130:131], 0
	v_mov_b64_e32 v[132:133], 0
	v_mov_b64_e32 v[134:135], 0
	v_mov_b64_e32 v[136:137], 0
	v_mov_b64_e32 v[138:139], 0
	v_mov_b64_e32 v[140:141], 0
	v_mov_b64_e32 v[142:143], 0

.LBB0_403:
	s_ashr_i32 s27, s26, 31
	s_lshl_b64 s[8:9], s[26:27], 19
	s_add_u32 s30, s56, s8
	s_addc_u32 s31, s57, s9
	s_and_b64 s[8:9], s[4:5], exec
	s_cselect_b32 s13, s31, s39
	s_cselect_b32 s27, s30, s38
	s_ashr_i32 s23, s22, 31
	s_lshl_b64 s[8:9], s[22:23], 19
	s_add_u32 s34, s68, s8
	s_addc_u32 s35, s69, s9
	s_and_b64 s[8:9], s[4:5], exec
	s_cselect_b32 s23, s35, s41
	s_cselect_b32 vcc_lo, s34, s40
	s_add_u32 s38, s38, 0x40080
	s_addc_u32 s39, s39, 0
	s_add_u32 vcc_hi, s40, 0x100
	v_mov_b32_e32 v0, 0
	s_addc_u32 s8, s41, 0
	s_mov_b32 s9, -2
	v_mov_b32_e32 v1, 0
	v_mov_b64_e32 v[2:3], 0
	v_mov_b64_e32 v[4:5], 0
	v_mov_b64_e32 v[6:7], 0
	v_mov_b64_e32 v[8:9], 0
	v_mov_b64_e32 v[10:11], 0
	v_mov_b64_e32 v[12:13], 0
	v_mov_b64_e32 v[14:15], 0
	v_mov_b64_e32 v[16:17], 0
	v_mov_b64_e32 v[18:19], 0
	v_mov_b64_e32 v[20:21], 0
	v_mov_b64_e32 v[22:23], 0
	v_mov_b64_e32 v[24:25], 0
	v_mov_b64_e32 v[26:27], 0
	v_mov_b64_e32 v[28:29], 0
	v_mov_b64_e32 v[30:31], 0
	v_mov_b64_e32 v[32:33], 0
	v_mov_b64_e32 v[34:35], 0
	v_mov_b64_e32 v[36:37], 0
	v_mov_b64_e32 v[38:39], 0
	v_mov_b64_e32 v[40:41], 0
	v_mov_b64_e32 v[42:43], 0
	v_mov_b64_e32 v[44:45], 0
	v_mov_b64_e32 v[46:47], 0
	v_mov_b64_e32 v[48:49], 0
	v_mov_b64_e32 v[50:51], 0
	v_mov_b64_e32 v[52:53], 0
	v_mov_b64_e32 v[54:55], 0
	v_mov_b64_e32 v[56:57], 0
	v_mov_b64_e32 v[58:59], 0
	v_mov_b64_e32 v[60:61], 0
	v_mov_b64_e32 v[62:63], 0
	v_mov_b64_e32 v[64:65], 0
	v_mov_b64_e32 v[66:67], 0
	v_mov_b64_e32 v[68:69], 0
	v_mov_b64_e32 v[70:71], 0
	v_mov_b64_e32 v[72:73], 0
	v_mov_b64_e32 v[74:75], 0
	v_mov_b64_e32 v[76:77], 0
	v_mov_b64_e32 v[78:79], 0
	v_mov_b64_e32 v[80:81], 0
	v_mov_b64_e32 v[82:83], 0
	v_mov_b64_e32 v[84:85], 0
	v_mov_b64_e32 v[86:87], 0
	v_mov_b64_e32 v[88:89], 0
	v_mov_b64_e32 v[90:91], 0
	v_mov_b64_e32 v[92:93], 0
	v_mov_b64_e32 v[94:95], 0
	v_mov_b64_e32 v[96:97], 0
	v_mov_b64_e32 v[98:99], 0
	v_mov_b64_e32 v[100:101], 0
	v_mov_b64_e32 v[102:103], 0
	v_mov_b64_e32 v[104:105], 0
	v_mov_b64_e32 v[106:107], 0
	v_mov_b64_e32 v[108:109], 0
	v_mov_b64_e32 v[110:111], 0
	v_mov_b64_e32 v[112:113], 0
	v_mov_b64_e32 v[114:115], 0
	v_mov_b64_e32 v[116:117], 0
	v_mov_b64_e32 v[118:119], 0
	v_mov_b64_e32 v[120:121], 0
	v_mov_b64_e32 v[122:123], 0
	v_mov_b64_e32 v[124:125], 0
	v_mov_b64_e32 v[126:127], 0

.LBB0_424:
	s_ashr_i32 s21, s20, 31
	s_lshl_b64 s[8:9], s[20:21], 19
	s_add_u32 s22, s79, s8
	s_addc_u32 s23, s84, s9
	s_and_b64 s[8:9], s[4:5], exec
	s_cselect_b32 s13, s23, s31
	s_cselect_b32 s21, s22, s30
	s_ashr_i32 s19, s18, 31
	s_lshl_b64 s[8:9], s[18:19], 19
	s_add_u32 s26, s56, s8
	s_addc_u32 s27, s57, s9
	s_and_b64 s[8:9], s[4:5], exec
	s_cselect_b32 s19, s27, s35
	s_cselect_b32 s74, s26, s34
	s_add_u32 s30, s30, 0x40080
	s_addc_u32 s31, s31, 0
	s_add_u32 s85, s34, 0x100
	v_mov_b32_e32 v0, 0
	s_addc_u32 s8, s35, 0
	s_mov_b32 s9, -2
	v_mov_b32_e32 v1, 0
	v_mov_b64_e32 v[2:3], 0
	v_mov_b64_e32 v[4:5], 0
	v_mov_b64_e32 v[6:7], 0
	v_mov_b64_e32 v[8:9], 0
	v_mov_b64_e32 v[10:11], 0
	v_mov_b64_e32 v[12:13], 0
	v_mov_b64_e32 v[14:15], 0
	v_mov_b64_e32 v[16:17], 0
	v_mov_b64_e32 v[18:19], 0
	v_mov_b64_e32 v[20:21], 0
	v_mov_b64_e32 v[22:23], 0
	v_mov_b64_e32 v[24:25], 0
	v_mov_b64_e32 v[26:27], 0
	v_mov_b64_e32 v[28:29], 0
	v_mov_b64_e32 v[30:31], 0
	v_mov_b64_e32 v[32:33], 0
	v_mov_b64_e32 v[34:35], 0
	v_mov_b64_e32 v[36:37], 0
	v_mov_b64_e32 v[38:39], 0
	v_mov_b64_e32 v[40:41], 0
	v_mov_b64_e32 v[42:43], 0
	v_mov_b64_e32 v[44:45], 0
	v_mov_b64_e32 v[46:47], 0
	v_mov_b64_e32 v[48:49], 0
	v_mov_b64_e32 v[50:51], 0
	v_mov_b64_e32 v[52:53], 0
	v_mov_b64_e32 v[54:55], 0
	v_mov_b64_e32 v[56:57], 0
	v_mov_b64_e32 v[58:59], 0
	v_mov_b64_e32 v[60:61], 0
	v_mov_b64_e32 v[62:63], 0
	v_mov_b64_e32 v[64:65], 0
	v_mov_b64_e32 v[66:67], 0
	v_mov_b64_e32 v[68:69], 0
	v_mov_b64_e32 v[70:71], 0
	v_mov_b64_e32 v[72:73], 0
	v_mov_b64_e32 v[74:75], 0
	v_mov_b64_e32 v[76:77], 0
	v_mov_b64_e32 v[78:79], 0
	v_mov_b64_e32 v[80:81], 0
	v_mov_b64_e32 v[82:83], 0
	v_mov_b64_e32 v[84:85], 0
	v_mov_b64_e32 v[86:87], 0
	v_mov_b64_e32 v[88:89], 0
	v_mov_b64_e32 v[90:91], 0
	v_mov_b64_e32 v[92:93], 0
	v_mov_b64_e32 v[94:95], 0
	v_mov_b64_e32 v[96:97], 0
	v_mov_b64_e32 v[98:99], 0
	v_mov_b64_e32 v[100:101], 0
	v_mov_b64_e32 v[102:103], 0
	v_mov_b64_e32 v[104:105], 0
	v_mov_b64_e32 v[106:107], 0
	v_mov_b64_e32 v[108:109], 0
	v_mov_b64_e32 v[110:111], 0
	v_mov_b64_e32 v[112:113], 0
	v_mov_b64_e32 v[114:115], 0
	v_mov_b64_e32 v[116:117], 0
	v_mov_b64_e32 v[118:119], 0
	v_mov_b64_e32 v[120:121], 0
	v_mov_b64_e32 v[122:123], 0
	v_mov_b64_e32 v[124:125], 0
	v_mov_b64_e32 v[126:127], 0

.LBB0_447:
	s_ashr_i32 s27, s26, 31
	s_lshl_b64 s[0:1], s[26:27], 19
	s_add_u32 s30, s79, s0
	s_addc_u32 s31, s84, s1
	s_and_b64 s[0:1], s[6:7], exec
	s_cselect_b32 s13, s31, s39
	s_cselect_b32 s27, s30, s38
	s_ashr_i32 s23, s22, 31
	s_lshl_b64 s[0:1], s[22:23], 19
	s_add_u32 s34, s56, s0
	s_addc_u32 s35, s57, s1
	s_and_b64 s[0:1], s[6:7], exec
	s_cselect_b32 s23, s35, s41
	s_cselect_b32 vcc_lo, s34, s40
	s_add_u32 s38, s38, 0x40080
	s_addc_u32 s39, s39, 0
	s_add_u32 vcc_hi, s40, 0x100
	v_mov_b32_e32 v0, 0
	s_addc_u32 s0, s41, 0
	s_mov_b32 s1, -2
	v_mov_b32_e32 v1, 0
	v_mov_b64_e32 v[2:3], 0
	v_mov_b64_e32 v[4:5], 0
	v_mov_b64_e32 v[6:7], 0
	v_mov_b64_e32 v[8:9], 0
	v_mov_b64_e32 v[10:11], 0
	v_mov_b64_e32 v[12:13], 0
	v_mov_b64_e32 v[14:15], 0
	v_mov_b64_e32 v[16:17], 0
	v_mov_b64_e32 v[18:19], 0
	v_mov_b64_e32 v[20:21], 0
	v_mov_b64_e32 v[22:23], 0
	v_mov_b64_e32 v[24:25], 0
	v_mov_b64_e32 v[26:27], 0
	v_mov_b64_e32 v[28:29], 0
	v_mov_b64_e32 v[30:31], 0
	v_mov_b64_e32 v[32:33], 0
	v_mov_b64_e32 v[34:35], 0
	v_mov_b64_e32 v[36:37], 0
	v_mov_b64_e32 v[38:39], 0
	v_mov_b64_e32 v[40:41], 0
	v_mov_b64_e32 v[42:43], 0
	v_mov_b64_e32 v[44:45], 0
	v_mov_b64_e32 v[46:47], 0
	v_mov_b64_e32 v[48:49], 0
	v_mov_b64_e32 v[50:51], 0
	v_mov_b64_e32 v[52:53], 0
	v_mov_b64_e32 v[54:55], 0
	v_mov_b64_e32 v[56:57], 0
	v_mov_b64_e32 v[58:59], 0
	v_mov_b64_e32 v[60:61], 0
	v_mov_b64_e32 v[62:63], 0
	v_mov_b64_e32 v[64:65], 0
	v_mov_b64_e32 v[66:67], 0
	v_mov_b64_e32 v[68:69], 0
	v_mov_b64_e32 v[70:71], 0
	v_mov_b64_e32 v[72:73], 0
	v_mov_b64_e32 v[74:75], 0
	v_mov_b64_e32 v[76:77], 0
	v_mov_b64_e32 v[78:79], 0
	v_mov_b64_e32 v[80:81], 0
	v_mov_b64_e32 v[82:83], 0
	v_mov_b64_e32 v[84:85], 0
	v_mov_b64_e32 v[86:87], 0
	v_mov_b64_e32 v[88:89], 0
	v_mov_b64_e32 v[90:91], 0
	v_mov_b64_e32 v[92:93], 0
	v_mov_b64_e32 v[94:95], 0
	v_mov_b64_e32 v[96:97], 0
	v_mov_b64_e32 v[98:99], 0
	v_mov_b64_e32 v[100:101], 0
	v_mov_b64_e32 v[102:103], 0
	v_mov_b64_e32 v[104:105], 0
	v_mov_b64_e32 v[106:107], 0
	v_mov_b64_e32 v[108:109], 0
	v_mov_b64_e32 v[110:111], 0
	v_mov_b64_e32 v[112:113], 0
	v_mov_b64_e32 v[114:115], 0
	v_mov_b64_e32 v[116:117], 0
	v_mov_b64_e32 v[118:119], 0
	v_mov_b64_e32 v[120:121], 0
	v_mov_b64_e32 v[122:123], 0
	v_mov_b64_e32 v[124:125], 0
	v_mov_b64_e32 v[126:127], 0

.LBB0_469:
	s_ashr_i32 s17, s16, 31
	s_lshl_b64 s[8:9], s[16:17], 19
	s_add_u32 s18, s56, s8
	s_addc_u32 s19, s57, s9
	s_and_b64 s[8:9], s[4:5], exec
	s_cselect_b32 s17, s19, s27
	s_cselect_b32 s51, s18, s26
	s_ashr_i32 s13, s12, 31
	s_lshl_b64 s[8:9], s[12:13], 19
	s_add_u32 s20, s68, s8
	s_addc_u32 s21, s69, s9
	s_and_b64 s[8:9], s[4:5], exec
	s_cselect_b32 s13, s21, s29
	s_cselect_b32 s54, s20, s28
	s_add_u32 s26, s26, 0x40080
	s_addc_u32 s27, s27, 0
	s_add_u32 s55, s28, 0x100
	v_mov_b32_e32 v0, 0
	s_addc_u32 s79, s29, 0
	s_mov_b32 s8, -2
	v_mov_b32_e32 v1, 0
	v_mov_b64_e32 v[2:3], 0
	v_mov_b64_e32 v[4:5], 0
	v_mov_b64_e32 v[6:7], 0
	v_mov_b64_e32 v[8:9], 0
	v_mov_b64_e32 v[10:11], 0
	v_mov_b64_e32 v[12:13], 0
	v_mov_b64_e32 v[14:15], 0
	v_mov_b64_e32 v[16:17], 0
	v_mov_b64_e32 v[18:19], 0
	v_mov_b64_e32 v[20:21], 0
	v_mov_b64_e32 v[22:23], 0
	v_mov_b64_e32 v[24:25], 0
	v_mov_b64_e32 v[26:27], 0
	v_mov_b64_e32 v[28:29], 0
	v_mov_b64_e32 v[30:31], 0
	v_mov_b64_e32 v[32:33], 0
	v_mov_b64_e32 v[34:35], 0
	v_mov_b64_e32 v[36:37], 0
	v_mov_b64_e32 v[38:39], 0
	v_mov_b64_e32 v[40:41], 0
	v_mov_b64_e32 v[42:43], 0
	v_mov_b64_e32 v[44:45], 0
	v_mov_b64_e32 v[46:47], 0
	v_mov_b64_e32 v[48:49], 0
	v_mov_b64_e32 v[50:51], 0
	v_mov_b64_e32 v[52:53], 0
	v_mov_b64_e32 v[54:55], 0
	v_mov_b64_e32 v[56:57], 0
	v_mov_b64_e32 v[58:59], 0
	v_mov_b64_e32 v[60:61], 0
	v_mov_b64_e32 v[62:63], 0
	v_mov_b64_e32 v[64:65], 0
	v_mov_b64_e32 v[66:67], 0
	v_mov_b64_e32 v[68:69], 0
	v_mov_b64_e32 v[70:71], 0
	v_mov_b64_e32 v[72:73], 0
	v_mov_b64_e32 v[74:75], 0
	v_mov_b64_e32 v[76:77], 0
	v_mov_b64_e32 v[78:79], 0
	v_mov_b64_e32 v[80:81], 0
	v_mov_b64_e32 v[82:83], 0
	v_mov_b64_e32 v[84:85], 0
	v_mov_b64_e32 v[86:87], 0
	v_mov_b64_e32 v[88:89], 0
	v_mov_b64_e32 v[90:91], 0
	v_mov_b64_e32 v[92:93], 0
	v_mov_b64_e32 v[94:95], 0
	v_mov_b64_e32 v[96:97], 0
	v_mov_b64_e32 v[98:99], 0
	v_mov_b64_e32 v[100:101], 0
	v_mov_b64_e32 v[102:103], 0
	v_mov_b64_e32 v[104:105], 0
	v_mov_b64_e32 v[106:107], 0
	v_mov_b64_e32 v[108:109], 0
	v_mov_b64_e32 v[110:111], 0
	v_mov_b64_e32 v[112:113], 0
	v_mov_b64_e32 v[114:115], 0
	v_mov_b64_e32 v[116:117], 0
	v_mov_b64_e32 v[118:119], 0
	v_mov_b64_e32 v[120:121], 0
	v_mov_b64_e32 v[122:123], 0
	v_mov_b64_e32 v[124:125], 0
	v_mov_b64_e32 v[126:127], 0

.LBB0_1195:
	v_mbcnt_lo_u32_b32 v154, -1, 0
	v_mbcnt_hi_u32_b32 v154, -1, v154
	s_lshl_b32 s24, s24, 8
	s_lshr_b32 s25, s33, 2
	s_lshl_b32 s25, s25, 6
	s_add_i32 s24, s24, s25
	v_and_b32_e32 v155, 15, v154
	v_lshrrev_b32_e32 v156, 4, v154
	v_add_u32_e32 v157, s24, v155
	s_lshl_b32 s24, s26, 8
	s_and_b32 s25, s33, 3
	s_lshl_b32 s25, s25, 5
	s_add_i32 s24, s24, s25
	v_lshl_add_u32 v158, v156, 3, s24
	v_lshlrev_b32_e32 v159, 11, v157
	v_lshl_add_u32 v159, v158, 1, v159
	v_lshlrev_b32_e32 v145, 1, v156
	v_and_b32_e32 v145, 2, v145
	v_lshrrev_b32_e32 v146, 1, v156
	v_or_b32_e32 v145, v145, v146
	v_lshl_add_u32 v144, v145, 4, v157
	v_lshlrev_b32_e32 v144, 2, v144
	v_mov_b32_e32 v224, v159
	v_add_u32_e32 v225, 0x8000, v159
	v_add_u32_e32 v226, 0x10000, v159
	v_add_u32_e32 v227, 0x18000, v159
	v_add_u32_e32 v228, 0x40000, v159
	v_add_u32_e32 v229, 0x48000, v159
	v_add_u32_e32 v230, 0x50000, v159
	v_add_u32_e32 v231, 0x58000, v159
	v_lshlrev_b32_e32 v232, 1, v224
	global_load_dwordx4 v[160:163], v232, s[36:37]
	global_load_dwordx4 v[164:167], v232, s[36:37] offset:16
	global_load_dwordx4 v[168:171], v232, s[36:37] offset:512
	global_load_dwordx4 v[172:175], v232, s[36:37] offset:528
	v_lshlrev_b32_e32 v233, 1, v225
	global_load_dwordx4 v[176:179], v233, s[36:37]
	global_load_dwordx4 v[180:183], v233, s[36:37] offset:16
	global_load_dwordx4 v[184:187], v233, s[36:37] offset:512
	global_load_dwordx4 v[188:191], v233, s[36:37] offset:528
	v_lshlrev_b32_e32 v234, 1, v226
	global_load_dwordx4 v[192:195], v234, s[36:37]
	global_load_dwordx4 v[196:199], v234, s[36:37] offset:16
	global_load_dwordx4 v[200:203], v234, s[36:37] offset:512
	global_load_dwordx4 v[204:207], v234, s[36:37] offset:528
	v_lshlrev_b32_e32 v235, 1, v227
	global_load_dwordx4 v[208:211], v235, s[36:37]
	global_load_dwordx4 v[212:215], v235, s[36:37] offset:16
	global_load_dwordx4 v[216:219], v235, s[36:37] offset:512
	global_load_dwordx4 v[220:223], v235, s[36:37] offset:528
	s_waitcnt vmcnt(0)
	v_pk_add_f32 v[124:125], v[124:125], v[160:161]
	v_pk_add_f32 v[126:127], v[126:127], v[162:163]
	v_pk_mul_f32 v[240:241], v[124:125], v[124:125]
	v_pk_fma_f32 v[240:241], v[126:127], v[126:127], v[240:241]
	v_pk_add_f32 v[120:121], v[120:121], v[164:165]
	v_pk_add_f32 v[122:123], v[122:123], v[166:167]
	v_pk_fma_f32 v[240:241], v[120:121], v[120:121], v[240:241]
	v_pk_fma_f32 v[240:241], v[122:123], v[122:123], v[240:241]
	v_cvt_pk_bf16_f32 v124, v124, v125
	v_cvt_pk_bf16_f32 v125, v126, v127
	v_cvt_pk_bf16_f32 v126, v120, v121
	v_cvt_pk_bf16_f32 v127, v122, v123
	global_store_dwordx4 v224, v[124:127], s[94:95]
	v_pk_add_f32 v[116:117], v[116:117], v[168:169]
	v_pk_add_f32 v[118:119], v[118:119], v[170:171]
	v_pk_fma_f32 v[240:241], v[116:117], v[116:117], v[240:241]
	v_pk_fma_f32 v[240:241], v[118:119], v[118:119], v[240:241]
	v_pk_add_f32 v[112:113], v[112:113], v[172:173]
	v_pk_add_f32 v[114:115], v[114:115], v[174:175]
	v_pk_fma_f32 v[240:241], v[112:113], v[112:113], v[240:241]
	v_pk_fma_f32 v[240:241], v[114:115], v[114:115], v[240:241]
	v_cvt_pk_bf16_f32 v116, v116, v117
	v_cvt_pk_bf16_f32 v117, v118, v119
	v_cvt_pk_bf16_f32 v118, v112, v113
	v_cvt_pk_bf16_f32 v119, v114, v115
	global_store_dwordx4 v224, v[116:119], s[94:95] offset:256
	v_add_f32_e32 v248, v240, v241
	v_lshlrev_b32_e32 v232, 1, v228
	global_load_dwordx4 v[160:163], v232, s[36:37]
	global_load_dwordx4 v[164:167], v232, s[36:37] offset:16
	global_load_dwordx4 v[168:171], v232, s[36:37] offset:512
	global_load_dwordx4 v[172:175], v232, s[36:37] offset:528
	v_pk_add_f32 v[108:109], v[108:109], v[176:177]
	v_pk_add_f32 v[110:111], v[110:111], v[178:179]
	v_pk_mul_f32 v[242:243], v[108:109], v[108:109]
	v_pk_fma_f32 v[242:243], v[110:111], v[110:111], v[242:243]
	v_pk_add_f32 v[104:105], v[104:105], v[180:181]
	v_pk_add_f32 v[106:107], v[106:107], v[182:183]
	v_pk_fma_f32 v[242:243], v[104:105], v[104:105], v[242:243]
	v_pk_fma_f32 v[242:243], v[106:107], v[106:107], v[242:243]
	v_cvt_pk_bf16_f32 v108, v108, v109
	v_cvt_pk_bf16_f32 v109, v110, v111
	v_cvt_pk_bf16_f32 v110, v104, v105
	v_cvt_pk_bf16_f32 v111, v106, v107
	global_store_dwordx4 v225, v[108:111], s[94:95]
	v_pk_add_f32 v[100:101], v[100:101], v[184:185]
	v_pk_add_f32 v[102:103], v[102:103], v[186:187]
	v_pk_fma_f32 v[242:243], v[100:101], v[100:101], v[242:243]
	v_pk_fma_f32 v[242:243], v[102:103], v[102:103], v[242:243]
	v_pk_add_f32 v[96:97], v[96:97], v[188:189]
	v_pk_add_f32 v[98:99], v[98:99], v[190:191]
	v_pk_fma_f32 v[242:243], v[96:97], v[96:97], v[242:243]
	v_pk_fma_f32 v[242:243], v[98:99], v[98:99], v[242:243]
	v_cvt_pk_bf16_f32 v100, v100, v101
	v_cvt_pk_bf16_f32 v101, v102, v103
	v_cvt_pk_bf16_f32 v102, v96, v97
	v_cvt_pk_bf16_f32 v103, v98, v99
	global_store_dwordx4 v225, v[100:103], s[94:95] offset:256
	v_add_f32_e32 v249, v242, v243
	v_lshlrev_b32_e32 v233, 1, v229
	global_load_dwordx4 v[176:179], v233, s[36:37]
	global_load_dwordx4 v[180:183], v233, s[36:37] offset:16
	global_load_dwordx4 v[184:187], v233, s[36:37] offset:512
	global_load_dwordx4 v[188:191], v233, s[36:37] offset:528
	v_pk_add_f32 v[92:93], v[92:93], v[192:193]
	v_pk_add_f32 v[94:95], v[94:95], v[194:195]
	v_pk_mul_f32 v[244:245], v[92:93], v[92:93]
	v_pk_fma_f32 v[244:245], v[94:95], v[94:95], v[244:245]
	v_pk_add_f32 v[88:89], v[88:89], v[196:197]
	v_pk_add_f32 v[90:91], v[90:91], v[198:199]
	v_pk_fma_f32 v[244:245], v[88:89], v[88:89], v[244:245]
	v_pk_fma_f32 v[244:245], v[90:91], v[90:91], v[244:245]
	v_cvt_pk_bf16_f32 v92, v92, v93
	v_cvt_pk_bf16_f32 v93, v94, v95
	v_cvt_pk_bf16_f32 v94, v88, v89
	v_cvt_pk_bf16_f32 v95, v90, v91
	global_store_dwordx4 v226, v[92:95], s[94:95]
	v_pk_add_f32 v[84:85], v[84:85], v[200:201]
	v_pk_add_f32 v[86:87], v[86:87], v[202:203]
	v_pk_fma_f32 v[244:245], v[84:85], v[84:85], v[244:245]
	v_pk_fma_f32 v[244:245], v[86:87], v[86:87], v[244:245]
	v_pk_add_f32 v[80:81], v[80:81], v[204:205]
	v_pk_add_f32 v[82:83], v[82:83], v[206:207]
	v_pk_fma_f32 v[244:245], v[80:81], v[80:81], v[244:245]
	v_pk_fma_f32 v[244:245], v[82:83], v[82:83], v[244:245]
	v_cvt_pk_bf16_f32 v84, v84, v85
	v_cvt_pk_bf16_f32 v85, v86, v87
	v_cvt_pk_bf16_f32 v86, v80, v81
	v_cvt_pk_bf16_f32 v87, v82, v83
	global_store_dwordx4 v226, v[84:87], s[94:95] offset:256
	v_add_f32_e32 v250, v244, v245
	v_lshlrev_b32_e32 v234, 1, v230
	global_load_dwordx4 v[192:195], v234, s[36:37]
	global_load_dwordx4 v[196:199], v234, s[36:37] offset:16
	global_load_dwordx4 v[200:203], v234, s[36:37] offset:512
	global_load_dwordx4 v[204:207], v234, s[36:37] offset:528
	v_pk_add_f32 v[76:77], v[76:77], v[208:209]
	v_pk_add_f32 v[78:79], v[78:79], v[210:211]
	v_pk_mul_f32 v[246:247], v[76:77], v[76:77]
	v_pk_fma_f32 v[246:247], v[78:79], v[78:79], v[246:247]
	v_pk_add_f32 v[72:73], v[72:73], v[212:213]
	v_pk_add_f32 v[74:75], v[74:75], v[214:215]
	v_pk_fma_f32 v[246:247], v[72:73], v[72:73], v[246:247]
	v_pk_fma_f32 v[246:247], v[74:75], v[74:75], v[246:247]
	v_cvt_pk_bf16_f32 v76, v76, v77
	v_cvt_pk_bf16_f32 v77, v78, v79
	v_cvt_pk_bf16_f32 v78, v72, v73
	v_cvt_pk_bf16_f32 v79, v74, v75
	global_store_dwordx4 v227, v[76:79], s[94:95]
	v_pk_add_f32 v[68:69], v[68:69], v[216:217]
	v_pk_add_f32 v[70:71], v[70:71], v[218:219]
	v_pk_fma_f32 v[246:247], v[68:69], v[68:69], v[246:247]
	v_pk_fma_f32 v[246:247], v[70:71], v[70:71], v[246:247]
	v_pk_add_f32 v[64:65], v[64:65], v[220:221]
	v_pk_add_f32 v[66:67], v[66:67], v[222:223]
	v_pk_fma_f32 v[246:247], v[64:65], v[64:65], v[246:247]
	v_pk_fma_f32 v[246:247], v[66:67], v[66:67], v[246:247]
	v_cvt_pk_bf16_f32 v68, v68, v69
	v_cvt_pk_bf16_f32 v69, v70, v71
	v_cvt_pk_bf16_f32 v70, v64, v65
	v_cvt_pk_bf16_f32 v71, v66, v67
	global_store_dwordx4 v227, v[68:71], s[94:95] offset:256
	v_add_f32_e32 v251, v246, v247
	v_lshlrev_b32_e32 v235, 1, v231
	global_load_dwordx4 v[208:211], v235, s[36:37]
	global_load_dwordx4 v[212:215], v235, s[36:37] offset:16
	global_load_dwordx4 v[216:219], v235, s[36:37] offset:512
	global_load_dwordx4 v[220:223], v235, s[36:37] offset:528
	s_nop 1
	v_permlane32_swap_b32_e32 v248, v249
	v_permlane32_swap_b32_e32 v250, v251
	v_add_f32_e32 v248, v248, v249
	v_add_f32_e32 v250, v250, v251
	s_nop 1
	v_permlane16_swap_b32_e32 v248, v250
	v_add_f32_e32 v248, v248, v250
	global_atomic_add_f32 v144, v248, s[10:11]
	s_waitcnt vmcnt(0)
	v_pk_add_f32 v[60:61], v[60:61], v[160:161]
	v_pk_add_f32 v[62:63], v[62:63], v[162:163]
	v_pk_mul_f32 v[240:241], v[60:61], v[60:61]
	v_pk_fma_f32 v[240:241], v[62:63], v[62:63], v[240:241]
	v_pk_add_f32 v[56:57], v[56:57], v[164:165]
	v_pk_add_f32 v[58:59], v[58:59], v[166:167]
	v_pk_fma_f32 v[240:241], v[56:57], v[56:57], v[240:241]
	v_pk_fma_f32 v[240:241], v[58:59], v[58:59], v[240:241]
	v_cvt_pk_bf16_f32 v60, v60, v61
	v_cvt_pk_bf16_f32 v61, v62, v63
	v_cvt_pk_bf16_f32 v62, v56, v57
	v_cvt_pk_bf16_f32 v63, v58, v59
	global_store_dwordx4 v228, v[60:63], s[94:95]
	v_pk_add_f32 v[52:53], v[52:53], v[168:169]
	v_pk_add_f32 v[54:55], v[54:55], v[170:171]
	v_pk_fma_f32 v[240:241], v[52:53], v[52:53], v[240:241]
	v_pk_fma_f32 v[240:241], v[54:55], v[54:55], v[240:241]
	v_pk_add_f32 v[48:49], v[48:49], v[172:173]
	v_pk_add_f32 v[50:51], v[50:51], v[174:175]
	v_pk_fma_f32 v[240:241], v[48:49], v[48:49], v[240:241]
	v_pk_fma_f32 v[240:241], v[50:51], v[50:51], v[240:241]
	v_cvt_pk_bf16_f32 v52, v52, v53
	v_cvt_pk_bf16_f32 v53, v54, v55
	v_cvt_pk_bf16_f32 v54, v48, v49
	v_cvt_pk_bf16_f32 v55, v50, v51
	global_store_dwordx4 v228, v[52:55], s[94:95] offset:256
	v_add_f32_e32 v248, v240, v241
	v_pk_add_f32 v[44:45], v[44:45], v[176:177]
	v_pk_add_f32 v[46:47], v[46:47], v[178:179]
	v_pk_mul_f32 v[242:243], v[44:45], v[44:45]
	v_pk_fma_f32 v[242:243], v[46:47], v[46:47], v[242:243]
	v_pk_add_f32 v[40:41], v[40:41], v[180:181]
	v_pk_add_f32 v[42:43], v[42:43], v[182:183]
	v_pk_fma_f32 v[242:243], v[40:41], v[40:41], v[242:243]
	v_pk_fma_f32 v[242:243], v[42:43], v[42:43], v[242:243]
	v_cvt_pk_bf16_f32 v44, v44, v45
	v_cvt_pk_bf16_f32 v45, v46, v47
	v_cvt_pk_bf16_f32 v46, v40, v41
	v_cvt_pk_bf16_f32 v47, v42, v43
	global_store_dwordx4 v229, v[44:47], s[94:95]
	v_pk_add_f32 v[36:37], v[36:37], v[184:185]
	v_pk_add_f32 v[38:39], v[38:39], v[186:187]
	v_pk_fma_f32 v[242:243], v[36:37], v[36:37], v[242:243]
	v_pk_fma_f32 v[242:243], v[38:39], v[38:39], v[242:243]
	v_pk_add_f32 v[32:33], v[32:33], v[188:189]
	v_pk_add_f32 v[34:35], v[34:35], v[190:191]
	v_pk_fma_f32 v[242:243], v[32:33], v[32:33], v[242:243]
	v_pk_fma_f32 v[242:243], v[34:35], v[34:35], v[242:243]
	v_cvt_pk_bf16_f32 v36, v36, v37
	v_cvt_pk_bf16_f32 v37, v38, v39
	v_cvt_pk_bf16_f32 v38, v32, v33
	v_cvt_pk_bf16_f32 v39, v34, v35
	global_store_dwordx4 v229, v[36:39], s[94:95] offset:256
	v_add_f32_e32 v249, v242, v243
	v_pk_add_f32 v[28:29], v[28:29], v[192:193]
	v_pk_add_f32 v[30:31], v[30:31], v[194:195]
	v_pk_mul_f32 v[244:245], v[28:29], v[28:29]
	v_pk_fma_f32 v[244:245], v[30:31], v[30:31], v[244:245]
	v_pk_add_f32 v[24:25], v[24:25], v[196:197]
	v_pk_add_f32 v[26:27], v[26:27], v[198:199]
	v_pk_fma_f32 v[244:245], v[24:25], v[24:25], v[244:245]
	v_pk_fma_f32 v[244:245], v[26:27], v[26:27], v[244:245]
	v_cvt_pk_bf16_f32 v28, v28, v29
	v_cvt_pk_bf16_f32 v29, v30, v31
	v_cvt_pk_bf16_f32 v30, v24, v25
	v_cvt_pk_bf16_f32 v31, v26, v27
	global_store_dwordx4 v230, v[28:31], s[94:95]
	v_pk_add_f32 v[20:21], v[20:21], v[200:201]
	v_pk_add_f32 v[22:23], v[22:23], v[202:203]
	v_pk_fma_f32 v[244:245], v[20:21], v[20:21], v[244:245]
	v_pk_fma_f32 v[244:245], v[22:23], v[22:23], v[244:245]
	v_pk_add_f32 v[16:17], v[16:17], v[204:205]
	v_pk_add_f32 v[18:19], v[18:19], v[206:207]
	v_pk_fma_f32 v[244:245], v[16:17], v[16:17], v[244:245]
	v_pk_fma_f32 v[244:245], v[18:19], v[18:19], v[244:245]
	v_cvt_pk_bf16_f32 v20, v20, v21
	v_cvt_pk_bf16_f32 v21, v22, v23
	v_cvt_pk_bf16_f32 v22, v16, v17
	v_cvt_pk_bf16_f32 v23, v18, v19
	global_store_dwordx4 v230, v[20:23], s[94:95] offset:256
	v_add_f32_e32 v250, v244, v245
	v_pk_add_f32 v[12:13], v[12:13], v[208:209]
	v_pk_add_f32 v[14:15], v[14:15], v[210:211]
	v_pk_mul_f32 v[246:247], v[12:13], v[12:13]
	v_pk_fma_f32 v[246:247], v[14:15], v[14:15], v[246:247]
	v_pk_add_f32 v[8:9], v[8:9], v[212:213]
	v_pk_add_f32 v[10:11], v[10:11], v[214:215]
	v_pk_fma_f32 v[246:247], v[8:9], v[8:9], v[246:247]
	v_pk_fma_f32 v[246:247], v[10:11], v[10:11], v[246:247]
	v_cvt_pk_bf16_f32 v12, v12, v13
	v_cvt_pk_bf16_f32 v13, v14, v15
	v_cvt_pk_bf16_f32 v14, v8, v9
	v_cvt_pk_bf16_f32 v15, v10, v11
	global_store_dwordx4 v231, v[12:15], s[94:95]
	v_pk_add_f32 v[4:5], v[4:5], v[216:217]
	v_pk_add_f32 v[6:7], v[6:7], v[218:219]
	v_pk_fma_f32 v[246:247], v[4:5], v[4:5], v[246:247]
	v_pk_fma_f32 v[246:247], v[6:7], v[6:7], v[246:247]
	v_pk_add_f32 v[0:1], v[0:1], v[220:221]
	v_pk_add_f32 v[2:3], v[2:3], v[222:223]
	v_pk_fma_f32 v[246:247], v[0:1], v[0:1], v[246:247]
	v_pk_fma_f32 v[246:247], v[2:3], v[2:3], v[246:247]
	v_cvt_pk_bf16_f32 v4, v4, v5
	v_cvt_pk_bf16_f32 v5, v6, v7
	v_cvt_pk_bf16_f32 v6, v0, v1
	v_cvt_pk_bf16_f32 v7, v2, v3
	global_store_dwordx4 v231, v[4:7], s[94:95] offset:256
	v_add_f32_e32 v251, v246, v247
	s_nop 1
	v_permlane32_swap_b32_e32 v248, v249
	v_permlane32_swap_b32_e32 v250, v251
	v_add_f32_e32 v248, v248, v249
	v_add_f32_e32 v250, v250, v251
	s_nop 1
	v_permlane16_swap_b32_e32 v248, v250
	v_add_f32_e32 v248, v248, v250
	global_atomic_add_f32 v144, v248, s[10:11] offset:512
	s_andn2_b64 vcc, exec, s[4:5]
	s_mov_b64 s[4:5], -1
	s_cbranch_vccnz .LBB0_1184
	s_andn2_b64 vcc, exec, s[8:9]
	s_cbranch_vccnz .LBB0_1183
	s_barrier
	s_branch .LBB0_1183

.LBB0_1282:
	s_ashr_i32 s19, s18, 31
	s_lshl_b64 s[24:25], s[18:19], 19
	s_add_u32 s24, s94, s24
	s_addc_u32 s25, s95, s25
	s_and_b64 s[26:27], s[4:5], exec
	s_cselect_b32 s19, s25, s31
	s_cselect_b32 s50, s24, s30
	s_ashr_i32 s17, s16, 31
	s_lshl_b64 s[26:27], s[16:17], 19
	s_add_u32 s26, s38, s26
	s_addc_u32 s27, s39, s27
	s_and_b64 s[36:37], s[4:5], exec
	s_cselect_b32 s17, s27, s35
	s_cselect_b32 s51, s26, s34
	s_add_u32 s30, s30, 0x40080
	s_addc_u32 s31, s31, 0
	s_add_u32 s52, s34, 0x100
	v_mov_b32_e32 v0, 0
	s_addc_u32 s53, s35, 0
	s_mov_b32 s54, -2
	v_mov_b32_e32 v1, 0
	v_mov_b64_e32 v[2:3], 0
	v_mov_b64_e32 v[4:5], 0
	v_mov_b64_e32 v[6:7], 0
	v_mov_b64_e32 v[8:9], 0
	v_mov_b64_e32 v[10:11], 0
	v_mov_b64_e32 v[12:13], 0
	v_mov_b64_e32 v[14:15], 0
	v_mov_b64_e32 v[16:17], 0
	v_mov_b64_e32 v[18:19], 0
	v_mov_b64_e32 v[20:21], 0
	v_mov_b64_e32 v[22:23], 0
	v_mov_b64_e32 v[24:25], 0
	v_mov_b64_e32 v[26:27], 0
	v_mov_b64_e32 v[28:29], 0
	v_mov_b64_e32 v[30:31], 0
	v_mov_b64_e32 v[32:33], 0
	v_mov_b64_e32 v[34:35], 0
	v_mov_b64_e32 v[36:37], 0
	v_mov_b64_e32 v[38:39], 0
	v_mov_b64_e32 v[40:41], 0
	v_mov_b64_e32 v[42:43], 0
	v_mov_b64_e32 v[44:45], 0
	v_mov_b64_e32 v[46:47], 0
	v_mov_b64_e32 v[48:49], 0
	v_mov_b64_e32 v[50:51], 0
	v_mov_b64_e32 v[52:53], 0
	v_mov_b64_e32 v[54:55], 0
	v_mov_b64_e32 v[56:57], 0
	v_mov_b64_e32 v[58:59], 0
	v_mov_b64_e32 v[60:61], 0
	v_mov_b64_e32 v[62:63], 0
	v_mov_b64_e32 v[64:65], 0
	v_mov_b64_e32 v[66:67], 0
	v_mov_b64_e32 v[68:69], 0
	v_mov_b64_e32 v[70:71], 0
	v_mov_b64_e32 v[72:73], 0
	v_mov_b64_e32 v[74:75], 0
	v_mov_b64_e32 v[76:77], 0
	v_mov_b64_e32 v[78:79], 0
	v_mov_b64_e32 v[80:81], 0
	v_mov_b64_e32 v[82:83], 0
	v_mov_b64_e32 v[84:85], 0
	v_mov_b64_e32 v[86:87], 0
	v_mov_b64_e32 v[88:89], 0
	v_mov_b64_e32 v[90:91], 0
	v_mov_b64_e32 v[92:93], 0
	v_mov_b64_e32 v[94:95], 0
	v_mov_b64_e32 v[96:97], 0
	v_mov_b64_e32 v[98:99], 0
	v_mov_b64_e32 v[100:101], 0
	v_mov_b64_e32 v[102:103], 0
	v_mov_b64_e32 v[104:105], 0
	v_mov_b64_e32 v[106:107], 0
	v_mov_b64_e32 v[108:109], 0
	v_mov_b64_e32 v[110:111], 0
	v_mov_b64_e32 v[112:113], 0
	v_mov_b64_e32 v[114:115], 0
	v_mov_b64_e32 v[116:117], 0
	v_mov_b64_e32 v[118:119], 0
	v_mov_b64_e32 v[120:121], 0
	v_mov_b64_e32 v[122:123], 0
	v_mov_b64_e32 v[124:125], 0
	v_mov_b64_e32 v[126:127], 0

.LBB0_1308:
	v_mov_b32_e32 v0, 0
	s_mov_b32 s29, 0
	s_mov_b64 s[42:43], -1
	s_mov_b64 s[44:45], 0
	s_waitcnt lgkmcnt(0)
	v_mov_b32_e32 v1, 0
	v_mov_b64_e32 v[2:3], 0
	v_mov_b64_e32 v[4:5], 0
	v_mov_b64_e32 v[6:7], 0
	v_mov_b64_e32 v[8:9], 0
	v_mov_b64_e32 v[10:11], 0
	v_mov_b64_e32 v[12:13], 0
	v_mov_b64_e32 v[14:15], 0
	v_mov_b64_e32 v[16:17], 0
	v_mov_b64_e32 v[18:19], 0
	v_mov_b64_e32 v[20:21], 0
	v_mov_b64_e32 v[22:23], 0
	v_mov_b64_e32 v[24:25], 0
	v_mov_b64_e32 v[26:27], 0
	v_mov_b64_e32 v[28:29], 0
	v_mov_b64_e32 v[30:31], 0
	v_mov_b64_e32 v[32:33], 0
	v_mov_b64_e32 v[34:35], 0
	v_mov_b64_e32 v[36:37], 0
	v_mov_b64_e32 v[38:39], 0
	v_mov_b64_e32 v[40:41], 0
	v_mov_b64_e32 v[42:43], 0
	v_mov_b64_e32 v[44:45], 0
	v_mov_b64_e32 v[46:47], 0
	v_mov_b64_e32 v[48:49], 0
	v_mov_b64_e32 v[50:51], 0
	v_mov_b64_e32 v[52:53], 0
	v_mov_b64_e32 v[54:55], 0
	v_mov_b64_e32 v[56:57], 0
	v_mov_b64_e32 v[58:59], 0
	v_mov_b64_e32 v[60:61], 0
	v_mov_b64_e32 v[62:63], 0
	v_mov_b64_e32 v[64:65], 0
	v_mov_b64_e32 v[66:67], 0
	v_mov_b64_e32 v[68:69], 0
	v_mov_b64_e32 v[70:71], 0
	v_mov_b64_e32 v[72:73], 0
	v_mov_b64_e32 v[74:75], 0
	v_mov_b64_e32 v[76:77], 0
	v_mov_b64_e32 v[78:79], 0
	v_mov_b64_e32 v[80:81], 0
	v_mov_b64_e32 v[82:83], 0
	v_mov_b64_e32 v[84:85], 0
	v_mov_b64_e32 v[86:87], 0
	v_mov_b64_e32 v[88:89], 0
	v_mov_b64_e32 v[90:91], 0
	v_mov_b64_e32 v[92:93], 0
	v_mov_b64_e32 v[94:95], 0
	v_mov_b64_e32 v[96:97], 0
	v_mov_b64_e32 v[98:99], 0
	v_mov_b64_e32 v[100:101], 0
	v_mov_b64_e32 v[102:103], 0
	v_mov_b64_e32 v[104:105], 0
	v_mov_b64_e32 v[106:107], 0
	v_mov_b64_e32 v[108:109], 0
	v_mov_b64_e32 v[110:111], 0
	v_mov_b64_e32 v[112:113], 0
	v_mov_b64_e32 v[114:115], 0
	v_mov_b64_e32 v[116:117], 0
	v_mov_b64_e32 v[118:119], 0
	v_mov_b64_e32 v[120:121], 0
	v_mov_b64_e32 v[122:123], 0
	v_mov_b64_e32 v[124:125], 0
	v_mov_b64_e32 v[126:127], 0

.LBB0_1348:
	v_mov_b32_e32 v0, 0
	s_mov_b32 s21, 0
	s_mov_b64 s[34:35], -1
	s_mov_b64 s[36:37], 0
	v_mov_b32_e32 v1, v0
	v_mov_b32_e32 v2, v0
	v_mov_b32_e32 v3, v0
	v_mov_b32_e32 v4, v0
	v_mov_b32_e32 v5, v0
	v_mov_b32_e32 v6, v0
	v_mov_b32_e32 v7, v0
	v_mov_b32_e32 v16, v0
	v_mov_b32_e32 v17, v0
	v_mov_b32_e32 v18, v0
	v_mov_b32_e32 v19, v0
	v_mov_b32_e32 v20, v0
	v_mov_b32_e32 v21, v0
	v_mov_b32_e32 v22, v0
	v_mov_b32_e32 v23, v0
	s_waitcnt vmcnt(0)
	v_mov_b64_e32 v[8:9], 0
	v_mov_b64_e32 v[10:11], 0
	v_mov_b64_e32 v[12:13], 0
	v_mov_b64_e32 v[14:15], 0
	v_mov_b64_e32 v[24:25], 0
	v_mov_b64_e32 v[26:27], 0
	v_mov_b64_e32 v[28:29], 0
	v_mov_b64_e32 v[30:31], 0
	v_mov_b64_e32 v[32:33], 0
	v_mov_b64_e32 v[34:35], 0
	v_mov_b64_e32 v[36:37], 0
	v_mov_b64_e32 v[38:39], 0
	v_mov_b64_e32 v[40:41], 0
	v_mov_b64_e32 v[42:43], 0
	v_mov_b64_e32 v[44:45], 0
	v_mov_b64_e32 v[46:47], 0
	v_mov_b64_e32 v[48:49], 0
	v_mov_b64_e32 v[50:51], 0
	v_mov_b64_e32 v[52:53], 0
	v_mov_b64_e32 v[54:55], 0
	v_mov_b64_e32 v[56:57], 0
	v_mov_b64_e32 v[58:59], 0
	v_mov_b64_e32 v[60:61], 0
	v_mov_b64_e32 v[62:63], 0
	v_mov_b64_e32 v[64:65], 0
	v_mov_b64_e32 v[66:67], 0
	v_mov_b64_e32 v[68:69], 0
	v_mov_b64_e32 v[70:71], 0
	v_mov_b64_e32 v[72:73], 0
	v_mov_b64_e32 v[74:75], 0
	v_mov_b64_e32 v[76:77], 0
	v_mov_b64_e32 v[78:79], 0
	v_mov_b64_e32 v[80:81], 0
	v_mov_b64_e32 v[82:83], 0
	v_mov_b64_e32 v[84:85], 0
	v_mov_b64_e32 v[86:87], 0
	v_mov_b64_e32 v[88:89], 0
	v_mov_b64_e32 v[90:91], 0
	v_mov_b64_e32 v[92:93], 0
	v_mov_b64_e32 v[94:95], 0
	v_mov_b64_e32 v[96:97], 0
	v_mov_b64_e32 v[98:99], 0
	v_mov_b64_e32 v[100:101], 0
	v_mov_b64_e32 v[102:103], 0
	v_mov_b64_e32 v[104:105], 0
	v_mov_b64_e32 v[106:107], 0
	v_mov_b64_e32 v[108:109], 0
	v_mov_b64_e32 v[110:111], 0
	v_mov_b64_e32 v[112:113], 0
	v_mov_b64_e32 v[114:115], 0
	v_mov_b64_e32 v[116:117], 0
	v_mov_b64_e32 v[118:119], 0
	v_mov_b64_e32 v[120:121], 0
	v_mov_b64_e32 v[122:123], 0
	v_mov_b64_e32 v[124:125], 0
	v_mov_b64_e32 v[126:127], 0

.LBB0_1425:
	s_ashr_i32 s19, s18, 31
	s_lshl_b64 s[20:21], s[18:19], 19
	s_add_u32 s20, s3, s20
	s_addc_u32 s21, s36, s21
	s_and_b64 s[22:23], s[4:5], exec
	s_cselect_b32 s19, s21, s29
	s_cselect_b32 s25, s20, s28
	s_ashr_i32 s17, s16, 31
	s_lshl_b64 s[22:23], s[16:17], 19
	s_add_u32 s22, s37, s22
	s_addc_u32 s23, s38, s23
	s_and_b64 s[34:35], s[4:5], exec
	s_cselect_b32 s17, s23, s31
	s_cselect_b32 s51, s22, s30
	s_add_u32 s28, s28, 0x40080
	s_addc_u32 s29, s29, 0
	s_add_u32 s52, s30, 0x100
	v_mov_b32_e32 v0, 0
	s_addc_u32 s53, s31, 0
	s_mov_b32 s54, -2
	s_waitcnt lgkmcnt(0)
	v_mov_b32_e32 v1, 0
	v_mov_b64_e32 v[2:3], 0
	v_mov_b64_e32 v[4:5], 0
	v_mov_b64_e32 v[6:7], 0
	v_mov_b64_e32 v[8:9], 0
	v_mov_b64_e32 v[10:11], 0
	v_mov_b64_e32 v[12:13], 0
	v_mov_b64_e32 v[14:15], 0
	v_mov_b64_e32 v[16:17], 0
	v_mov_b64_e32 v[18:19], 0
	v_mov_b64_e32 v[20:21], 0
	v_mov_b64_e32 v[22:23], 0
	v_mov_b64_e32 v[24:25], 0
	v_mov_b64_e32 v[26:27], 0
	v_mov_b64_e32 v[28:29], 0
	v_mov_b64_e32 v[30:31], 0
	v_mov_b64_e32 v[32:33], 0
	v_mov_b64_e32 v[34:35], 0
	v_mov_b64_e32 v[36:37], 0
	v_mov_b64_e32 v[38:39], 0
	v_mov_b64_e32 v[40:41], 0
	v_mov_b64_e32 v[42:43], 0
	v_mov_b64_e32 v[44:45], 0
	v_mov_b64_e32 v[46:47], 0
	v_mov_b64_e32 v[48:49], 0
	v_mov_b64_e32 v[50:51], 0
	v_mov_b64_e32 v[52:53], 0
	v_mov_b64_e32 v[54:55], 0
	v_mov_b64_e32 v[56:57], 0
	v_mov_b64_e32 v[58:59], 0
	v_mov_b64_e32 v[60:61], 0
	v_mov_b64_e32 v[62:63], 0
	v_mov_b64_e32 v[64:65], 0
	v_mov_b64_e32 v[66:67], 0
	v_mov_b64_e32 v[68:69], 0
	v_mov_b64_e32 v[70:71], 0
	v_mov_b64_e32 v[72:73], 0
	v_mov_b64_e32 v[74:75], 0
	v_mov_b64_e32 v[76:77], 0
	v_mov_b64_e32 v[78:79], 0
	v_mov_b64_e32 v[80:81], 0
	v_mov_b64_e32 v[82:83], 0
	v_mov_b64_e32 v[84:85], 0
	v_mov_b64_e32 v[86:87], 0
	v_mov_b64_e32 v[88:89], 0
	v_mov_b64_e32 v[90:91], 0
	v_mov_b64_e32 v[92:93], 0
	v_mov_b64_e32 v[94:95], 0
	v_mov_b64_e32 v[96:97], 0
	v_mov_b64_e32 v[98:99], 0
	v_mov_b64_e32 v[100:101], 0
	v_mov_b64_e32 v[102:103], 0
	v_mov_b64_e32 v[104:105], 0
	v_mov_b64_e32 v[106:107], 0
	v_mov_b64_e32 v[108:109], 0
	v_mov_b64_e32 v[110:111], 0
	v_mov_b64_e32 v[112:113], 0
	v_mov_b64_e32 v[114:115], 0
	v_mov_b64_e32 v[116:117], 0
	v_mov_b64_e32 v[118:119], 0
	v_mov_b64_e32 v[120:121], 0
	v_mov_b64_e32 v[122:123], 0
	v_mov_b64_e32 v[124:125], 0
	v_mov_b64_e32 v[126:127], 0

.LBB0_1429:
	v_mbcnt_lo_u32_b32 v154, -1, 0
	v_mbcnt_hi_u32_b32 v154, -1, v154
	s_lshl_b32 s24, s24, 8
	s_lshr_b32 s25, s33, 2
	s_lshl_b32 s25, s25, 6
	s_add_i32 s24, s24, s25
	v_and_b32_e32 v155, 15, v154
	v_lshrrev_b32_e32 v156, 4, v154
	v_add_u32_e32 v157, s24, v155
	s_lshl_b32 s24, s26, 8
	s_and_b32 s25, s33, 3
	s_lshl_b32 s25, s25, 5
	s_add_i32 s24, s24, s25
	v_lshl_add_u32 v158, v156, 3, s24
	v_lshlrev_b32_e32 v159, 11, v157
	v_lshl_add_u32 v159, v158, 1, v159
	v_lshlrev_b32_e32 v145, 1, v156
	v_and_b32_e32 v145, 2, v145
	v_lshrrev_b32_e32 v146, 1, v156
	v_or_b32_e32 v145, v145, v146
	v_lshl_add_u32 v144, v145, 4, v157
	v_lshlrev_b32_e32 v144, 2, v144
	v_mov_b32_e32 v224, v159
	v_add_u32_e32 v225, 0x8000, v159
	v_add_u32_e32 v226, 0x10000, v159
	v_add_u32_e32 v227, 0x18000, v159
	v_add_u32_e32 v228, 0x40000, v159
	v_add_u32_e32 v229, 0x48000, v159
	v_add_u32_e32 v230, 0x50000, v159
	v_add_u32_e32 v231, 0x58000, v159
	global_load_dwordx4 v[160:163], v224, s[94:95]
	global_load_dwordx4 v[164:167], v224, s[94:95] offset:256
	global_load_dwordx4 v[168:171], v225, s[94:95]
	global_load_dwordx4 v[172:175], v225, s[94:95] offset:256
	global_load_dwordx4 v[176:179], v226, s[94:95]
	global_load_dwordx4 v[180:183], v226, s[94:95] offset:256
	global_load_dwordx4 v[184:187], v227, s[94:95]
	global_load_dwordx4 v[188:191], v227, s[94:95] offset:256
	global_load_dwordx4 v[192:195], v228, s[94:95]
	global_load_dwordx4 v[196:199], v228, s[94:95] offset:256
	global_load_dwordx4 v[200:203], v229, s[94:95]
	global_load_dwordx4 v[204:207], v229, s[94:95] offset:256
	global_load_dwordx4 v[208:211], v230, s[94:95]
	global_load_dwordx4 v[212:215], v230, s[94:95] offset:256
	global_load_dwordx4 v[216:219], v231, s[94:95]
	global_load_dwordx4 v[220:223], v231, s[94:95] offset:256
	s_waitcnt vmcnt(0)
	v_lshlrev_b32_e32 v232, 16, v160
	v_and_b32_e32 v233, 0xffff0000, v160
	v_lshlrev_b32_e32 v234, 16, v161
	v_and_b32_e32 v235, 0xffff0000, v161
	v_pk_add_f32 v[124:125], v[124:125], v[232:233]
	v_pk_add_f32 v[126:127], v[126:127], v[234:235]
	v_pk_mul_f32 v[240:241], v[124:125], v[124:125]
	v_pk_fma_f32 v[240:241], v[126:127], v[126:127], v[240:241]
	v_lshlrev_b32_e32 v236, 16, v162
	v_and_b32_e32 v237, 0xffff0000, v162
	v_lshlrev_b32_e32 v238, 16, v163
	v_and_b32_e32 v239, 0xffff0000, v163
	v_pk_add_f32 v[120:121], v[120:121], v[236:237]
	v_pk_add_f32 v[122:123], v[122:123], v[238:239]
	v_pk_fma_f32 v[240:241], v[120:121], v[120:121], v[240:241]
	v_pk_fma_f32 v[240:241], v[122:123], v[122:123], v[240:241]
	v_cvt_pk_bf16_f32 v124, v124, v125
	v_cvt_pk_bf16_f32 v125, v126, v127
	v_cvt_pk_bf16_f32 v126, v120, v121
	v_cvt_pk_bf16_f32 v127, v122, v123
	global_store_dwordx4 v224, v[124:127], s[94:95]
	v_lshlrev_b32_e32 v232, 16, v164
	v_and_b32_e32 v233, 0xffff0000, v164
	v_lshlrev_b32_e32 v234, 16, v165
	v_and_b32_e32 v235, 0xffff0000, v165
	v_pk_add_f32 v[116:117], v[116:117], v[232:233]
	v_pk_add_f32 v[118:119], v[118:119], v[234:235]
	v_pk_fma_f32 v[240:241], v[116:117], v[116:117], v[240:241]
	v_pk_fma_f32 v[240:241], v[118:119], v[118:119], v[240:241]
	v_lshlrev_b32_e32 v236, 16, v166
	v_and_b32_e32 v237, 0xffff0000, v166
	v_lshlrev_b32_e32 v238, 16, v167
	v_and_b32_e32 v239, 0xffff0000, v167
	v_pk_add_f32 v[112:113], v[112:113], v[236:237]
	v_pk_add_f32 v[114:115], v[114:115], v[238:239]
	v_pk_fma_f32 v[240:241], v[112:113], v[112:113], v[240:241]
	v_pk_fma_f32 v[240:241], v[114:115], v[114:115], v[240:241]
	v_cvt_pk_bf16_f32 v116, v116, v117
	v_cvt_pk_bf16_f32 v117, v118, v119
	v_cvt_pk_bf16_f32 v118, v112, v113
	v_cvt_pk_bf16_f32 v119, v114, v115
	global_store_dwordx4 v224, v[116:119], s[94:95] offset:256
	v_add_f32_e32 v248, v240, v241
	v_lshlrev_b32_e32 v232, 16, v168
	v_and_b32_e32 v233, 0xffff0000, v168
	v_lshlrev_b32_e32 v234, 16, v169
	v_and_b32_e32 v235, 0xffff0000, v169
	v_pk_add_f32 v[108:109], v[108:109], v[232:233]
	v_pk_add_f32 v[110:111], v[110:111], v[234:235]
	v_pk_mul_f32 v[242:243], v[108:109], v[108:109]
	v_pk_fma_f32 v[242:243], v[110:111], v[110:111], v[242:243]
	v_lshlrev_b32_e32 v236, 16, v170
	v_and_b32_e32 v237, 0xffff0000, v170
	v_lshlrev_b32_e32 v238, 16, v171
	v_and_b32_e32 v239, 0xffff0000, v171
	v_pk_add_f32 v[104:105], v[104:105], v[236:237]
	v_pk_add_f32 v[106:107], v[106:107], v[238:239]
	v_pk_fma_f32 v[242:243], v[104:105], v[104:105], v[242:243]
	v_pk_fma_f32 v[242:243], v[106:107], v[106:107], v[242:243]
	v_cvt_pk_bf16_f32 v108, v108, v109
	v_cvt_pk_bf16_f32 v109, v110, v111
	v_cvt_pk_bf16_f32 v110, v104, v105
	v_cvt_pk_bf16_f32 v111, v106, v107
	global_store_dwordx4 v225, v[108:111], s[94:95]
	v_lshlrev_b32_e32 v232, 16, v172
	v_and_b32_e32 v233, 0xffff0000, v172
	v_lshlrev_b32_e32 v234, 16, v173
	v_and_b32_e32 v235, 0xffff0000, v173
	v_pk_add_f32 v[100:101], v[100:101], v[232:233]
	v_pk_add_f32 v[102:103], v[102:103], v[234:235]
	v_pk_fma_f32 v[242:243], v[100:101], v[100:101], v[242:243]
	v_pk_fma_f32 v[242:243], v[102:103], v[102:103], v[242:243]
	v_lshlrev_b32_e32 v236, 16, v174
	v_and_b32_e32 v237, 0xffff0000, v174
	v_lshlrev_b32_e32 v238, 16, v175
	v_and_b32_e32 v239, 0xffff0000, v175
	v_pk_add_f32 v[96:97], v[96:97], v[236:237]
	v_pk_add_f32 v[98:99], v[98:99], v[238:239]
	v_pk_fma_f32 v[242:243], v[96:97], v[96:97], v[242:243]
	v_pk_fma_f32 v[242:243], v[98:99], v[98:99], v[242:243]
	v_cvt_pk_bf16_f32 v100, v100, v101
	v_cvt_pk_bf16_f32 v101, v102, v103
	v_cvt_pk_bf16_f32 v102, v96, v97
	v_cvt_pk_bf16_f32 v103, v98, v99
	global_store_dwordx4 v225, v[100:103], s[94:95] offset:256
	v_add_f32_e32 v249, v242, v243
	v_lshlrev_b32_e32 v232, 16, v176
	v_and_b32_e32 v233, 0xffff0000, v176
	v_lshlrev_b32_e32 v234, 16, v177
	v_and_b32_e32 v235, 0xffff0000, v177
	v_pk_add_f32 v[92:93], v[92:93], v[232:233]
	v_pk_add_f32 v[94:95], v[94:95], v[234:235]
	v_pk_mul_f32 v[244:245], v[92:93], v[92:93]
	v_pk_fma_f32 v[244:245], v[94:95], v[94:95], v[244:245]
	v_lshlrev_b32_e32 v236, 16, v178
	v_and_b32_e32 v237, 0xffff0000, v178
	v_lshlrev_b32_e32 v238, 16, v179
	v_and_b32_e32 v239, 0xffff0000, v179
	v_pk_add_f32 v[88:89], v[88:89], v[236:237]
	v_pk_add_f32 v[90:91], v[90:91], v[238:239]
	v_pk_fma_f32 v[244:245], v[88:89], v[88:89], v[244:245]
	v_pk_fma_f32 v[244:245], v[90:91], v[90:91], v[244:245]
	v_cvt_pk_bf16_f32 v92, v92, v93
	v_cvt_pk_bf16_f32 v93, v94, v95
	v_cvt_pk_bf16_f32 v94, v88, v89
	v_cvt_pk_bf16_f32 v95, v90, v91
	global_store_dwordx4 v226, v[92:95], s[94:95]
	v_lshlrev_b32_e32 v232, 16, v180
	v_and_b32_e32 v233, 0xffff0000, v180
	v_lshlrev_b32_e32 v234, 16, v181
	v_and_b32_e32 v235, 0xffff0000, v181
	v_pk_add_f32 v[84:85], v[84:85], v[232:233]
	v_pk_add_f32 v[86:87], v[86:87], v[234:235]
	v_pk_fma_f32 v[244:245], v[84:85], v[84:85], v[244:245]
	v_pk_fma_f32 v[244:245], v[86:87], v[86:87], v[244:245]
	v_lshlrev_b32_e32 v236, 16, v182
	v_and_b32_e32 v237, 0xffff0000, v182
	v_lshlrev_b32_e32 v238, 16, v183
	v_and_b32_e32 v239, 0xffff0000, v183
	v_pk_add_f32 v[80:81], v[80:81], v[236:237]
	v_pk_add_f32 v[82:83], v[82:83], v[238:239]
	v_pk_fma_f32 v[244:245], v[80:81], v[80:81], v[244:245]
	v_pk_fma_f32 v[244:245], v[82:83], v[82:83], v[244:245]
	v_cvt_pk_bf16_f32 v84, v84, v85
	v_cvt_pk_bf16_f32 v85, v86, v87
	v_cvt_pk_bf16_f32 v86, v80, v81
	v_cvt_pk_bf16_f32 v87, v82, v83
	global_store_dwordx4 v226, v[84:87], s[94:95] offset:256
	v_add_f32_e32 v250, v244, v245
	v_lshlrev_b32_e32 v232, 16, v184
	v_and_b32_e32 v233, 0xffff0000, v184
	v_lshlrev_b32_e32 v234, 16, v185
	v_and_b32_e32 v235, 0xffff0000, v185
	v_pk_add_f32 v[76:77], v[76:77], v[232:233]
	v_pk_add_f32 v[78:79], v[78:79], v[234:235]
	v_pk_mul_f32 v[246:247], v[76:77], v[76:77]
	v_pk_fma_f32 v[246:247], v[78:79], v[78:79], v[246:247]
	v_lshlrev_b32_e32 v236, 16, v186
	v_and_b32_e32 v237, 0xffff0000, v186
	v_lshlrev_b32_e32 v238, 16, v187
	v_and_b32_e32 v239, 0xffff0000, v187
	v_pk_add_f32 v[72:73], v[72:73], v[236:237]
	v_pk_add_f32 v[74:75], v[74:75], v[238:239]
	v_pk_fma_f32 v[246:247], v[72:73], v[72:73], v[246:247]
	v_pk_fma_f32 v[246:247], v[74:75], v[74:75], v[246:247]
	v_cvt_pk_bf16_f32 v76, v76, v77
	v_cvt_pk_bf16_f32 v77, v78, v79
	v_cvt_pk_bf16_f32 v78, v72, v73
	v_cvt_pk_bf16_f32 v79, v74, v75
	global_store_dwordx4 v227, v[76:79], s[94:95]
	v_lshlrev_b32_e32 v232, 16, v188
	v_and_b32_e32 v233, 0xffff0000, v188
	v_lshlrev_b32_e32 v234, 16, v189
	v_and_b32_e32 v235, 0xffff0000, v189
	v_pk_add_f32 v[68:69], v[68:69], v[232:233]
	v_pk_add_f32 v[70:71], v[70:71], v[234:235]
	v_pk_fma_f32 v[246:247], v[68:69], v[68:69], v[246:247]
	v_pk_fma_f32 v[246:247], v[70:71], v[70:71], v[246:247]
	v_lshlrev_b32_e32 v236, 16, v190
	v_and_b32_e32 v237, 0xffff0000, v190
	v_lshlrev_b32_e32 v238, 16, v191
	v_and_b32_e32 v239, 0xffff0000, v191
	v_pk_add_f32 v[64:65], v[64:65], v[236:237]
	v_pk_add_f32 v[66:67], v[66:67], v[238:239]
	v_pk_fma_f32 v[246:247], v[64:65], v[64:65], v[246:247]
	v_pk_fma_f32 v[246:247], v[66:67], v[66:67], v[246:247]
	v_cvt_pk_bf16_f32 v68, v68, v69
	v_cvt_pk_bf16_f32 v69, v70, v71
	v_cvt_pk_bf16_f32 v70, v64, v65
	v_cvt_pk_bf16_f32 v71, v66, v67
	global_store_dwordx4 v227, v[68:71], s[94:95] offset:256
	v_add_f32_e32 v251, v246, v247
	s_nop 1
	v_permlane32_swap_b32_e32 v248, v249
	v_permlane32_swap_b32_e32 v250, v251
	v_add_f32_e32 v248, v248, v249
	v_add_f32_e32 v250, v250, v251
	s_nop 1
	v_permlane16_swap_b32_e32 v248, v250
	v_add_f32_e32 v248, v248, v250
	global_atomic_add_f32 v144, v248, s[10:11]
	v_lshlrev_b32_e32 v232, 16, v192
	v_and_b32_e32 v233, 0xffff0000, v192
	v_lshlrev_b32_e32 v234, 16, v193
	v_and_b32_e32 v235, 0xffff0000, v193
	v_pk_add_f32 v[60:61], v[60:61], v[232:233]
	v_pk_add_f32 v[62:63], v[62:63], v[234:235]
	v_pk_mul_f32 v[240:241], v[60:61], v[60:61]
	v_pk_fma_f32 v[240:241], v[62:63], v[62:63], v[240:241]
	v_lshlrev_b32_e32 v236, 16, v194
	v_and_b32_e32 v237, 0xffff0000, v194
	v_lshlrev_b32_e32 v238, 16, v195
	v_and_b32_e32 v239, 0xffff0000, v195
	v_pk_add_f32 v[56:57], v[56:57], v[236:237]
	v_pk_add_f32 v[58:59], v[58:59], v[238:239]
	v_pk_fma_f32 v[240:241], v[56:57], v[56:57], v[240:241]
	v_pk_fma_f32 v[240:241], v[58:59], v[58:59], v[240:241]
	v_cvt_pk_bf16_f32 v60, v60, v61
	v_cvt_pk_bf16_f32 v61, v62, v63
	v_cvt_pk_bf16_f32 v62, v56, v57
	v_cvt_pk_bf16_f32 v63, v58, v59
	global_store_dwordx4 v228, v[60:63], s[94:95]
	v_lshlrev_b32_e32 v232, 16, v196
	v_and_b32_e32 v233, 0xffff0000, v196
	v_lshlrev_b32_e32 v234, 16, v197
	v_and_b32_e32 v235, 0xffff0000, v197
	v_pk_add_f32 v[52:53], v[52:53], v[232:233]
	v_pk_add_f32 v[54:55], v[54:55], v[234:235]
	v_pk_fma_f32 v[240:241], v[52:53], v[52:53], v[240:241]
	v_pk_fma_f32 v[240:241], v[54:55], v[54:55], v[240:241]
	v_lshlrev_b32_e32 v236, 16, v198
	v_and_b32_e32 v237, 0xffff0000, v198
	v_lshlrev_b32_e32 v238, 16, v199
	v_and_b32_e32 v239, 0xffff0000, v199
	v_pk_add_f32 v[48:49], v[48:49], v[236:237]
	v_pk_add_f32 v[50:51], v[50:51], v[238:239]
	v_pk_fma_f32 v[240:241], v[48:49], v[48:49], v[240:241]
	v_pk_fma_f32 v[240:241], v[50:51], v[50:51], v[240:241]
	v_cvt_pk_bf16_f32 v52, v52, v53
	v_cvt_pk_bf16_f32 v53, v54, v55
	v_cvt_pk_bf16_f32 v54, v48, v49
	v_cvt_pk_bf16_f32 v55, v50, v51
	global_store_dwordx4 v228, v[52:55], s[94:95] offset:256
	v_add_f32_e32 v248, v240, v241
	v_lshlrev_b32_e32 v232, 16, v200
	v_and_b32_e32 v233, 0xffff0000, v200
	v_lshlrev_b32_e32 v234, 16, v201
	v_and_b32_e32 v235, 0xffff0000, v201
	v_pk_add_f32 v[44:45], v[44:45], v[232:233]
	v_pk_add_f32 v[46:47], v[46:47], v[234:235]
	v_pk_mul_f32 v[242:243], v[44:45], v[44:45]
	v_pk_fma_f32 v[242:243], v[46:47], v[46:47], v[242:243]
	v_lshlrev_b32_e32 v236, 16, v202
	v_and_b32_e32 v237, 0xffff0000, v202
	v_lshlrev_b32_e32 v238, 16, v203
	v_and_b32_e32 v239, 0xffff0000, v203
	v_pk_add_f32 v[40:41], v[40:41], v[236:237]
	v_pk_add_f32 v[42:43], v[42:43], v[238:239]
	v_pk_fma_f32 v[242:243], v[40:41], v[40:41], v[242:243]
	v_pk_fma_f32 v[242:243], v[42:43], v[42:43], v[242:243]
	v_cvt_pk_bf16_f32 v44, v44, v45
	v_cvt_pk_bf16_f32 v45, v46, v47
	v_cvt_pk_bf16_f32 v46, v40, v41
	v_cvt_pk_bf16_f32 v47, v42, v43
	global_store_dwordx4 v229, v[44:47], s[94:95]
	v_lshlrev_b32_e32 v232, 16, v204
	v_and_b32_e32 v233, 0xffff0000, v204
	v_lshlrev_b32_e32 v234, 16, v205
	v_and_b32_e32 v235, 0xffff0000, v205
	v_pk_add_f32 v[36:37], v[36:37], v[232:233]
	v_pk_add_f32 v[38:39], v[38:39], v[234:235]
	v_pk_fma_f32 v[242:243], v[36:37], v[36:37], v[242:243]
	v_pk_fma_f32 v[242:243], v[38:39], v[38:39], v[242:243]
	v_lshlrev_b32_e32 v236, 16, v206
	v_and_b32_e32 v237, 0xffff0000, v206
	v_lshlrev_b32_e32 v238, 16, v207
	v_and_b32_e32 v239, 0xffff0000, v207
	v_pk_add_f32 v[32:33], v[32:33], v[236:237]
	v_pk_add_f32 v[34:35], v[34:35], v[238:239]
	v_pk_fma_f32 v[242:243], v[32:33], v[32:33], v[242:243]
	v_pk_fma_f32 v[242:243], v[34:35], v[34:35], v[242:243]
	v_cvt_pk_bf16_f32 v36, v36, v37
	v_cvt_pk_bf16_f32 v37, v38, v39
	v_cvt_pk_bf16_f32 v38, v32, v33
	v_cvt_pk_bf16_f32 v39, v34, v35
	global_store_dwordx4 v229, v[36:39], s[94:95] offset:256
	v_add_f32_e32 v249, v242, v243
	v_lshlrev_b32_e32 v232, 16, v208
	v_and_b32_e32 v233, 0xffff0000, v208
	v_lshlrev_b32_e32 v234, 16, v209
	v_and_b32_e32 v235, 0xffff0000, v209
	v_pk_add_f32 v[28:29], v[28:29], v[232:233]
	v_pk_add_f32 v[30:31], v[30:31], v[234:235]
	v_pk_mul_f32 v[244:245], v[28:29], v[28:29]
	v_pk_fma_f32 v[244:245], v[30:31], v[30:31], v[244:245]
	v_lshlrev_b32_e32 v236, 16, v210
	v_and_b32_e32 v237, 0xffff0000, v210
	v_lshlrev_b32_e32 v238, 16, v211
	v_and_b32_e32 v239, 0xffff0000, v211
	v_pk_add_f32 v[24:25], v[24:25], v[236:237]
	v_pk_add_f32 v[26:27], v[26:27], v[238:239]
	v_pk_fma_f32 v[244:245], v[24:25], v[24:25], v[244:245]
	v_pk_fma_f32 v[244:245], v[26:27], v[26:27], v[244:245]
	v_cvt_pk_bf16_f32 v28, v28, v29
	v_cvt_pk_bf16_f32 v29, v30, v31
	v_cvt_pk_bf16_f32 v30, v24, v25
	v_cvt_pk_bf16_f32 v31, v26, v27
	global_store_dwordx4 v230, v[28:31], s[94:95]
	v_lshlrev_b32_e32 v232, 16, v212
	v_and_b32_e32 v233, 0xffff0000, v212
	v_lshlrev_b32_e32 v234, 16, v213
	v_and_b32_e32 v235, 0xffff0000, v213
	v_pk_add_f32 v[20:21], v[20:21], v[232:233]
	v_pk_add_f32 v[22:23], v[22:23], v[234:235]
	v_pk_fma_f32 v[244:245], v[20:21], v[20:21], v[244:245]
	v_pk_fma_f32 v[244:245], v[22:23], v[22:23], v[244:245]
	v_lshlrev_b32_e32 v236, 16, v214
	v_and_b32_e32 v237, 0xffff0000, v214
	v_lshlrev_b32_e32 v238, 16, v215
	v_and_b32_e32 v239, 0xffff0000, v215
	v_pk_add_f32 v[16:17], v[16:17], v[236:237]
	v_pk_add_f32 v[18:19], v[18:19], v[238:239]
	v_pk_fma_f32 v[244:245], v[16:17], v[16:17], v[244:245]
	v_pk_fma_f32 v[244:245], v[18:19], v[18:19], v[244:245]
	v_cvt_pk_bf16_f32 v20, v20, v21
	v_cvt_pk_bf16_f32 v21, v22, v23
	v_cvt_pk_bf16_f32 v22, v16, v17
	v_cvt_pk_bf16_f32 v23, v18, v19
	global_store_dwordx4 v230, v[20:23], s[94:95] offset:256
	v_add_f32_e32 v250, v244, v245
	v_lshlrev_b32_e32 v232, 16, v216
	v_and_b32_e32 v233, 0xffff0000, v216
	v_lshlrev_b32_e32 v234, 16, v217
	v_and_b32_e32 v235, 0xffff0000, v217
	v_pk_add_f32 v[12:13], v[12:13], v[232:233]
	v_pk_add_f32 v[14:15], v[14:15], v[234:235]
	v_pk_mul_f32 v[246:247], v[12:13], v[12:13]
	v_pk_fma_f32 v[246:247], v[14:15], v[14:15], v[246:247]
	v_lshlrev_b32_e32 v236, 16, v218
	v_and_b32_e32 v237, 0xffff0000, v218
	v_lshlrev_b32_e32 v238, 16, v219
	v_and_b32_e32 v239, 0xffff0000, v219
	v_pk_add_f32 v[8:9], v[8:9], v[236:237]
	v_pk_add_f32 v[10:11], v[10:11], v[238:239]
	v_pk_fma_f32 v[246:247], v[8:9], v[8:9], v[246:247]
	v_pk_fma_f32 v[246:247], v[10:11], v[10:11], v[246:247]
	v_cvt_pk_bf16_f32 v12, v12, v13
	v_cvt_pk_bf16_f32 v13, v14, v15
	v_cvt_pk_bf16_f32 v14, v8, v9
	v_cvt_pk_bf16_f32 v15, v10, v11
	global_store_dwordx4 v231, v[12:15], s[94:95]
	v_lshlrev_b32_e32 v232, 16, v220
	v_and_b32_e32 v233, 0xffff0000, v220
	v_lshlrev_b32_e32 v234, 16, v221
	v_and_b32_e32 v235, 0xffff0000, v221
	v_pk_add_f32 v[4:5], v[4:5], v[232:233]
	v_pk_add_f32 v[6:7], v[6:7], v[234:235]
	v_pk_fma_f32 v[246:247], v[4:5], v[4:5], v[246:247]
	v_pk_fma_f32 v[246:247], v[6:7], v[6:7], v[246:247]
	v_lshlrev_b32_e32 v236, 16, v222
	v_and_b32_e32 v237, 0xffff0000, v222
	v_lshlrev_b32_e32 v238, 16, v223
	v_and_b32_e32 v239, 0xffff0000, v223
	v_pk_add_f32 v[0:1], v[0:1], v[236:237]
	v_pk_add_f32 v[2:3], v[2:3], v[238:239]
	v_pk_fma_f32 v[246:247], v[0:1], v[0:1], v[246:247]
	v_pk_fma_f32 v[246:247], v[2:3], v[2:3], v[246:247]
	v_cvt_pk_bf16_f32 v4, v4, v5
	v_cvt_pk_bf16_f32 v5, v6, v7
	v_cvt_pk_bf16_f32 v6, v0, v1
	v_cvt_pk_bf16_f32 v7, v2, v3
	global_store_dwordx4 v231, v[4:7], s[94:95] offset:256
	v_add_f32_e32 v251, v246, v247
	s_nop 1
	v_permlane32_swap_b32_e32 v248, v249
	v_permlane32_swap_b32_e32 v250, v251
	v_add_f32_e32 v248, v248, v249
	v_add_f32_e32 v250, v250, v251
	s_nop 1
	v_permlane16_swap_b32_e32 v248, v250
	v_add_f32_e32 v248, v248, v250
	global_atomic_add_f32 v144, v248, s[10:11] offset:512
	s_andn2_b64 vcc, exec, s[4:5]
	s_mov_b64 s[4:5], -1
	s_cbranch_vccnz .LBB0_1418
	s_andn2_b64 vcc, exec, s[8:9]
	s_cbranch_vccnz .LBB0_1417
	s_barrier
	s_branch .LBB0_1417

.LBB0_1514:
	s_ashr_i32 s57, s56, 31
	s_lshl_b64 s[12:13], s[56:57], 19
	s_add_u32 s58, s94, s12
	s_addc_u32 s59, s95, s13
	s_and_b64 s[12:13], s[0:1], exec
	s_cselect_b32 s5, s59, s9
	s_cselect_b32 s7, s58, s8
	s_ashr_i32 s55, s54, 31
	s_lshl_b64 s[12:13], s[54:55], 19
	s_add_u32 s60, s3, s12
	s_addc_u32 s61, s62, s13
	s_and_b64 s[12:13], s[0:1], exec
	s_cselect_b32 s14, s61, s11
	s_cselect_b32 s15, s60, s10
	s_add_u32 s8, s8, 0x40080
	s_addc_u32 s9, s9, 0
	s_add_u32 s16, s10, 0x100
	v_mov_b32_e32 v0, 0
	s_addc_u32 s17, s11, 0
	s_mov_b32 s18, -2
	v_mov_b32_e32 v1, 0
	v_mov_b64_e32 v[2:3], 0
	v_mov_b64_e32 v[4:5], 0
	v_mov_b64_e32 v[6:7], 0
	v_mov_b64_e32 v[8:9], 0
	v_mov_b64_e32 v[10:11], 0
	v_mov_b64_e32 v[12:13], 0
	v_mov_b64_e32 v[14:15], 0
	v_mov_b64_e32 v[16:17], 0
	v_mov_b64_e32 v[18:19], 0
	v_mov_b64_e32 v[20:21], 0
	v_mov_b64_e32 v[22:23], 0
	v_mov_b64_e32 v[24:25], 0
	v_mov_b64_e32 v[26:27], 0
	v_mov_b64_e32 v[28:29], 0
	v_mov_b64_e32 v[30:31], 0
	v_mov_b64_e32 v[32:33], 0
	v_mov_b64_e32 v[34:35], 0
	v_mov_b64_e32 v[36:37], 0
	v_mov_b64_e32 v[38:39], 0
	v_mov_b64_e32 v[40:41], 0
	v_mov_b64_e32 v[42:43], 0
	v_mov_b64_e32 v[44:45], 0
	v_mov_b64_e32 v[46:47], 0
	v_mov_b64_e32 v[48:49], 0
	v_mov_b64_e32 v[50:51], 0
	v_mov_b64_e32 v[52:53], 0
	v_mov_b64_e32 v[54:55], 0
	v_mov_b64_e32 v[56:57], 0
	v_mov_b64_e32 v[58:59], 0
	v_mov_b64_e32 v[60:61], 0
	v_mov_b64_e32 v[62:63], 0
	v_mov_b64_e32 v[64:65], 0
	v_mov_b64_e32 v[66:67], 0
	v_mov_b64_e32 v[68:69], 0
	v_mov_b64_e32 v[70:71], 0
	v_mov_b64_e32 v[72:73], 0
	v_mov_b64_e32 v[74:75], 0
	v_mov_b64_e32 v[76:77], 0
	v_mov_b64_e32 v[78:79], 0
	v_mov_b64_e32 v[80:81], 0
	v_mov_b64_e32 v[82:83], 0
	v_mov_b64_e32 v[84:85], 0
	v_mov_b64_e32 v[86:87], 0
	v_mov_b64_e32 v[88:89], 0
	v_mov_b64_e32 v[90:91], 0
	v_mov_b64_e32 v[92:93], 0
	v_mov_b64_e32 v[94:95], 0
	v_mov_b64_e32 v[96:97], 0
	v_mov_b64_e32 v[98:99], 0
	v_mov_b64_e32 v[100:101], 0
	v_mov_b64_e32 v[102:103], 0
	v_mov_b64_e32 v[104:105], 0
	v_mov_b64_e32 v[106:107], 0
	v_mov_b64_e32 v[108:109], 0
	v_mov_b64_e32 v[110:111], 0
	v_mov_b64_e32 v[112:113], 0
	v_mov_b64_e32 v[114:115], 0
	v_mov_b64_e32 v[116:117], 0
	v_mov_b64_e32 v[118:119], 0
	v_mov_b64_e32 v[120:121], 0
	v_mov_b64_e32 v[122:123], 0
	v_mov_b64_e32 v[124:125], 0
	v_mov_b64_e32 v[126:127], 0

.LBB0_1704:
	s_add_u32 s52, s24, 0x100
	v_mov_b32_e32 v0, 0
	s_addc_u32 s53, s25, 0
	s_mov_b32 s54, -2
	s_waitcnt lgkmcnt(0)
	v_mov_b32_e32 v1, 0
	v_mov_b64_e32 v[2:3], 0
	v_mov_b64_e32 v[4:5], 0
	v_mov_b64_e32 v[6:7], 0
	v_mov_b64_e32 v[8:9], 0
	v_mov_b64_e32 v[10:11], 0
	v_mov_b64_e32 v[12:13], 0
	v_mov_b64_e32 v[14:15], 0
	v_mov_b64_e32 v[16:17], 0
	v_mov_b64_e32 v[18:19], 0
	v_mov_b64_e32 v[20:21], 0
	v_mov_b64_e32 v[22:23], 0
	v_mov_b64_e32 v[24:25], 0
	v_mov_b64_e32 v[26:27], 0
	v_mov_b64_e32 v[28:29], 0
	v_mov_b64_e32 v[30:31], 0
	v_mov_b64_e32 v[32:33], 0
	v_mov_b64_e32 v[34:35], 0
	v_mov_b64_e32 v[36:37], 0
	v_mov_b64_e32 v[38:39], 0
	v_mov_b64_e32 v[40:41], 0
	v_mov_b64_e32 v[42:43], 0
	v_mov_b64_e32 v[44:45], 0
	v_mov_b64_e32 v[46:47], 0
	v_mov_b64_e32 v[48:49], 0
	v_mov_b64_e32 v[50:51], 0
	v_mov_b64_e32 v[52:53], 0
	v_mov_b64_e32 v[54:55], 0
	v_mov_b64_e32 v[56:57], 0
	v_mov_b64_e32 v[58:59], 0
	v_mov_b64_e32 v[60:61], 0
	v_mov_b64_e32 v[62:63], 0
	v_mov_b64_e32 v[64:65], 0
	v_mov_b64_e32 v[66:67], 0
	v_mov_b64_e32 v[68:69], 0
	v_mov_b64_e32 v[70:71], 0
	v_mov_b64_e32 v[72:73], 0
	v_mov_b64_e32 v[74:75], 0
	v_mov_b64_e32 v[76:77], 0
	v_mov_b64_e32 v[78:79], 0
	v_mov_b64_e32 v[80:81], 0
	v_mov_b64_e32 v[82:83], 0
	v_mov_b64_e32 v[84:85], 0
	v_mov_b64_e32 v[86:87], 0
	v_mov_b64_e32 v[88:89], 0
	v_mov_b64_e32 v[90:91], 0
	v_mov_b64_e32 v[92:93], 0
	v_mov_b64_e32 v[94:95], 0
	v_mov_b64_e32 v[96:97], 0
	v_mov_b64_e32 v[98:99], 0
	v_mov_b64_e32 v[100:101], 0
	v_mov_b64_e32 v[102:103], 0
	v_mov_b64_e32 v[104:105], 0
	v_mov_b64_e32 v[106:107], 0
	v_mov_b64_e32 v[108:109], 0
	v_mov_b64_e32 v[110:111], 0
	v_mov_b64_e32 v[112:113], 0
	v_mov_b64_e32 v[114:115], 0
	v_mov_b64_e32 v[116:117], 0
	v_mov_b64_e32 v[118:119], 0
	v_mov_b64_e32 v[120:121], 0
	v_mov_b64_e32 v[122:123], 0
	v_mov_b64_e32 v[124:125], 0
	v_mov_b64_e32 v[126:127], 0

.LBB0_1708:
	v_mbcnt_lo_u32_b32 v154, -1, 0
	v_mbcnt_hi_u32_b32 v154, -1, v154
	s_lshl_b32 s22, s51, 8
	s_lshr_b32 s23, s33, 2
	s_lshl_b32 s23, s23, 6
	s_add_i32 s22, s22, s23
	v_and_b32_e32 v155, 15, v154
	v_lshrrev_b32_e32 v156, 4, v154
	v_add_u32_e32 v157, s22, v155
	s_lshl_b32 s22, s50, 8
	s_and_b32 s23, s33, 3
	s_lshl_b32 s23, s23, 5
	s_add_i32 s22, s22, s23
	v_lshl_add_u32 v158, v156, 3, s22
	v_lshlrev_b32_e32 v159, 11, v157
	v_lshl_add_u32 v159, v158, 1, v159
	v_lshlrev_b32_e32 v145, 1, v156
	v_and_b32_e32 v145, 2, v145
	v_lshrrev_b32_e32 v146, 1, v156
	v_or_b32_e32 v145, v145, v146
	v_lshl_add_u32 v144, v145, 4, v157
	v_lshlrev_b32_e32 v144, 2, v144
	v_mov_b32_e32 v224, v159
	v_add_u32_e32 v225, 0x8000, v159
	v_add_u32_e32 v226, 0x10000, v159
	v_add_u32_e32 v227, 0x18000, v159
	v_add_u32_e32 v228, 0x40000, v159
	v_add_u32_e32 v229, 0x48000, v159
	v_add_u32_e32 v230, 0x50000, v159
	v_add_u32_e32 v231, 0x58000, v159
	global_load_dwordx4 v[160:163], v224, s[94:95]
	global_load_dwordx4 v[164:167], v224, s[94:95] offset:256
	global_load_dwordx4 v[168:171], v225, s[94:95]
	global_load_dwordx4 v[172:175], v225, s[94:95] offset:256
	global_load_dwordx4 v[176:179], v226, s[94:95]
	global_load_dwordx4 v[180:183], v226, s[94:95] offset:256
	global_load_dwordx4 v[184:187], v227, s[94:95]
	global_load_dwordx4 v[188:191], v227, s[94:95] offset:256
	global_load_dwordx4 v[192:195], v228, s[94:95]
	global_load_dwordx4 v[196:199], v228, s[94:95] offset:256
	global_load_dwordx4 v[200:203], v229, s[94:95]
	global_load_dwordx4 v[204:207], v229, s[94:95] offset:256
	global_load_dwordx4 v[208:211], v230, s[94:95]
	global_load_dwordx4 v[212:215], v230, s[94:95] offset:256
	global_load_dwordx4 v[216:219], v231, s[94:95]
	global_load_dwordx4 v[220:223], v231, s[94:95] offset:256
	s_waitcnt vmcnt(0)
	v_lshlrev_b32_e32 v232, 16, v160
	v_and_b32_e32 v233, 0xffff0000, v160
	v_lshlrev_b32_e32 v234, 16, v161
	v_and_b32_e32 v235, 0xffff0000, v161
	v_pk_add_f32 v[124:125], v[124:125], v[232:233]
	v_pk_add_f32 v[126:127], v[126:127], v[234:235]
	v_pk_mul_f32 v[240:241], v[124:125], v[124:125]
	v_pk_fma_f32 v[240:241], v[126:127], v[126:127], v[240:241]
	v_lshlrev_b32_e32 v236, 16, v162
	v_and_b32_e32 v237, 0xffff0000, v162
	v_lshlrev_b32_e32 v238, 16, v163
	v_and_b32_e32 v239, 0xffff0000, v163
	v_pk_add_f32 v[120:121], v[120:121], v[236:237]
	v_pk_add_f32 v[122:123], v[122:123], v[238:239]
	v_pk_fma_f32 v[240:241], v[120:121], v[120:121], v[240:241]
	v_pk_fma_f32 v[240:241], v[122:123], v[122:123], v[240:241]
	v_cvt_pk_bf16_f32 v124, v124, v125
	v_cvt_pk_bf16_f32 v125, v126, v127
	v_cvt_pk_bf16_f32 v126, v120, v121
	v_cvt_pk_bf16_f32 v127, v122, v123
	global_store_dwordx4 v224, v[124:127], s[12:13]
	v_lshlrev_b32_e32 v232, 16, v164
	v_and_b32_e32 v233, 0xffff0000, v164
	v_lshlrev_b32_e32 v234, 16, v165
	v_and_b32_e32 v235, 0xffff0000, v165
	v_pk_add_f32 v[116:117], v[116:117], v[232:233]
	v_pk_add_f32 v[118:119], v[118:119], v[234:235]
	v_pk_fma_f32 v[240:241], v[116:117], v[116:117], v[240:241]
	v_pk_fma_f32 v[240:241], v[118:119], v[118:119], v[240:241]
	v_lshlrev_b32_e32 v236, 16, v166
	v_and_b32_e32 v237, 0xffff0000, v166
	v_lshlrev_b32_e32 v238, 16, v167
	v_and_b32_e32 v239, 0xffff0000, v167
	v_pk_add_f32 v[112:113], v[112:113], v[236:237]
	v_pk_add_f32 v[114:115], v[114:115], v[238:239]
	v_pk_fma_f32 v[240:241], v[112:113], v[112:113], v[240:241]
	v_pk_fma_f32 v[240:241], v[114:115], v[114:115], v[240:241]
	v_cvt_pk_bf16_f32 v116, v116, v117
	v_cvt_pk_bf16_f32 v117, v118, v119
	v_cvt_pk_bf16_f32 v118, v112, v113
	v_cvt_pk_bf16_f32 v119, v114, v115
	global_store_dwordx4 v224, v[116:119], s[12:13] offset:256
	v_add_f32_e32 v248, v240, v241
	v_lshlrev_b32_e32 v232, 16, v168
	v_and_b32_e32 v233, 0xffff0000, v168
	v_lshlrev_b32_e32 v234, 16, v169
	v_and_b32_e32 v235, 0xffff0000, v169
	v_pk_add_f32 v[108:109], v[108:109], v[232:233]
	v_pk_add_f32 v[110:111], v[110:111], v[234:235]
	v_pk_mul_f32 v[242:243], v[108:109], v[108:109]
	v_pk_fma_f32 v[242:243], v[110:111], v[110:111], v[242:243]
	v_lshlrev_b32_e32 v236, 16, v170
	v_and_b32_e32 v237, 0xffff0000, v170
	v_lshlrev_b32_e32 v238, 16, v171
	v_and_b32_e32 v239, 0xffff0000, v171
	v_pk_add_f32 v[104:105], v[104:105], v[236:237]
	v_pk_add_f32 v[106:107], v[106:107], v[238:239]
	v_pk_fma_f32 v[242:243], v[104:105], v[104:105], v[242:243]
	v_pk_fma_f32 v[242:243], v[106:107], v[106:107], v[242:243]
	v_cvt_pk_bf16_f32 v108, v108, v109
	v_cvt_pk_bf16_f32 v109, v110, v111
	v_cvt_pk_bf16_f32 v110, v104, v105
	v_cvt_pk_bf16_f32 v111, v106, v107
	global_store_dwordx4 v225, v[108:111], s[12:13]
	v_lshlrev_b32_e32 v232, 16, v172
	v_and_b32_e32 v233, 0xffff0000, v172
	v_lshlrev_b32_e32 v234, 16, v173
	v_and_b32_e32 v235, 0xffff0000, v173
	v_pk_add_f32 v[100:101], v[100:101], v[232:233]
	v_pk_add_f32 v[102:103], v[102:103], v[234:235]
	v_pk_fma_f32 v[242:243], v[100:101], v[100:101], v[242:243]
	v_pk_fma_f32 v[242:243], v[102:103], v[102:103], v[242:243]
	v_lshlrev_b32_e32 v236, 16, v174
	v_and_b32_e32 v237, 0xffff0000, v174
	v_lshlrev_b32_e32 v238, 16, v175
	v_and_b32_e32 v239, 0xffff0000, v175
	v_pk_add_f32 v[96:97], v[96:97], v[236:237]
	v_pk_add_f32 v[98:99], v[98:99], v[238:239]
	v_pk_fma_f32 v[242:243], v[96:97], v[96:97], v[242:243]
	v_pk_fma_f32 v[242:243], v[98:99], v[98:99], v[242:243]
	v_cvt_pk_bf16_f32 v100, v100, v101
	v_cvt_pk_bf16_f32 v101, v102, v103
	v_cvt_pk_bf16_f32 v102, v96, v97
	v_cvt_pk_bf16_f32 v103, v98, v99
	global_store_dwordx4 v225, v[100:103], s[12:13] offset:256
	v_add_f32_e32 v249, v242, v243
	v_lshlrev_b32_e32 v232, 16, v176
	v_and_b32_e32 v233, 0xffff0000, v176
	v_lshlrev_b32_e32 v234, 16, v177
	v_and_b32_e32 v235, 0xffff0000, v177
	v_pk_add_f32 v[92:93], v[92:93], v[232:233]
	v_pk_add_f32 v[94:95], v[94:95], v[234:235]
	v_pk_mul_f32 v[244:245], v[92:93], v[92:93]
	v_pk_fma_f32 v[244:245], v[94:95], v[94:95], v[244:245]
	v_lshlrev_b32_e32 v236, 16, v178
	v_and_b32_e32 v237, 0xffff0000, v178
	v_lshlrev_b32_e32 v238, 16, v179
	v_and_b32_e32 v239, 0xffff0000, v179
	v_pk_add_f32 v[88:89], v[88:89], v[236:237]
	v_pk_add_f32 v[90:91], v[90:91], v[238:239]
	v_pk_fma_f32 v[244:245], v[88:89], v[88:89], v[244:245]
	v_pk_fma_f32 v[244:245], v[90:91], v[90:91], v[244:245]
	v_cvt_pk_bf16_f32 v92, v92, v93
	v_cvt_pk_bf16_f32 v93, v94, v95
	v_cvt_pk_bf16_f32 v94, v88, v89
	v_cvt_pk_bf16_f32 v95, v90, v91
	global_store_dwordx4 v226, v[92:95], s[12:13]
	v_lshlrev_b32_e32 v232, 16, v180
	v_and_b32_e32 v233, 0xffff0000, v180
	v_lshlrev_b32_e32 v234, 16, v181
	v_and_b32_e32 v235, 0xffff0000, v181
	v_pk_add_f32 v[84:85], v[84:85], v[232:233]
	v_pk_add_f32 v[86:87], v[86:87], v[234:235]
	v_pk_fma_f32 v[244:245], v[84:85], v[84:85], v[244:245]
	v_pk_fma_f32 v[244:245], v[86:87], v[86:87], v[244:245]
	v_lshlrev_b32_e32 v236, 16, v182
	v_and_b32_e32 v237, 0xffff0000, v182
	v_lshlrev_b32_e32 v238, 16, v183
	v_and_b32_e32 v239, 0xffff0000, v183
	v_pk_add_f32 v[80:81], v[80:81], v[236:237]
	v_pk_add_f32 v[82:83], v[82:83], v[238:239]
	v_pk_fma_f32 v[244:245], v[80:81], v[80:81], v[244:245]
	v_pk_fma_f32 v[244:245], v[82:83], v[82:83], v[244:245]
	v_cvt_pk_bf16_f32 v84, v84, v85
	v_cvt_pk_bf16_f32 v85, v86, v87
	v_cvt_pk_bf16_f32 v86, v80, v81
	v_cvt_pk_bf16_f32 v87, v82, v83
	global_store_dwordx4 v226, v[84:87], s[12:13] offset:256
	v_add_f32_e32 v250, v244, v245
	v_lshlrev_b32_e32 v232, 16, v184
	v_and_b32_e32 v233, 0xffff0000, v184
	v_lshlrev_b32_e32 v234, 16, v185
	v_and_b32_e32 v235, 0xffff0000, v185
	v_pk_add_f32 v[76:77], v[76:77], v[232:233]
	v_pk_add_f32 v[78:79], v[78:79], v[234:235]
	v_pk_mul_f32 v[246:247], v[76:77], v[76:77]
	v_pk_fma_f32 v[246:247], v[78:79], v[78:79], v[246:247]
	v_lshlrev_b32_e32 v236, 16, v186
	v_and_b32_e32 v237, 0xffff0000, v186
	v_lshlrev_b32_e32 v238, 16, v187
	v_and_b32_e32 v239, 0xffff0000, v187
	v_pk_add_f32 v[72:73], v[72:73], v[236:237]
	v_pk_add_f32 v[74:75], v[74:75], v[238:239]
	v_pk_fma_f32 v[246:247], v[72:73], v[72:73], v[246:247]
	v_pk_fma_f32 v[246:247], v[74:75], v[74:75], v[246:247]
	v_cvt_pk_bf16_f32 v76, v76, v77
	v_cvt_pk_bf16_f32 v77, v78, v79
	v_cvt_pk_bf16_f32 v78, v72, v73
	v_cvt_pk_bf16_f32 v79, v74, v75
	global_store_dwordx4 v227, v[76:79], s[12:13]
	v_lshlrev_b32_e32 v232, 16, v188
	v_and_b32_e32 v233, 0xffff0000, v188
	v_lshlrev_b32_e32 v234, 16, v189
	v_and_b32_e32 v235, 0xffff0000, v189
	v_pk_add_f32 v[68:69], v[68:69], v[232:233]
	v_pk_add_f32 v[70:71], v[70:71], v[234:235]
	v_pk_fma_f32 v[246:247], v[68:69], v[68:69], v[246:247]
	v_pk_fma_f32 v[246:247], v[70:71], v[70:71], v[246:247]
	v_lshlrev_b32_e32 v236, 16, v190
	v_and_b32_e32 v237, 0xffff0000, v190
	v_lshlrev_b32_e32 v238, 16, v191
	v_and_b32_e32 v239, 0xffff0000, v191
	v_pk_add_f32 v[64:65], v[64:65], v[236:237]
	v_pk_add_f32 v[66:67], v[66:67], v[238:239]
	v_pk_fma_f32 v[246:247], v[64:65], v[64:65], v[246:247]
	v_pk_fma_f32 v[246:247], v[66:67], v[66:67], v[246:247]
	v_cvt_pk_bf16_f32 v68, v68, v69
	v_cvt_pk_bf16_f32 v69, v70, v71
	v_cvt_pk_bf16_f32 v70, v64, v65
	v_cvt_pk_bf16_f32 v71, v66, v67
	global_store_dwordx4 v227, v[68:71], s[12:13] offset:256
	v_add_f32_e32 v251, v246, v247
	s_nop 1
	v_permlane32_swap_b32_e32 v248, v249
	v_permlane32_swap_b32_e32 v250, v251
	v_add_f32_e32 v248, v248, v249
	v_add_f32_e32 v250, v250, v251
	s_nop 1
	v_permlane16_swap_b32_e32 v248, v250
	v_add_f32_e32 v248, v248, v250
	global_atomic_add_f32 v144, v248, s[14:15]
	v_lshlrev_b32_e32 v232, 16, v192
	v_and_b32_e32 v233, 0xffff0000, v192
	v_lshlrev_b32_e32 v234, 16, v193
	v_and_b32_e32 v235, 0xffff0000, v193
	v_pk_add_f32 v[60:61], v[60:61], v[232:233]
	v_pk_add_f32 v[62:63], v[62:63], v[234:235]
	v_pk_mul_f32 v[240:241], v[60:61], v[60:61]
	v_pk_fma_f32 v[240:241], v[62:63], v[62:63], v[240:241]
	v_lshlrev_b32_e32 v236, 16, v194
	v_and_b32_e32 v237, 0xffff0000, v194
	v_lshlrev_b32_e32 v238, 16, v195
	v_and_b32_e32 v239, 0xffff0000, v195
	v_pk_add_f32 v[56:57], v[56:57], v[236:237]
	v_pk_add_f32 v[58:59], v[58:59], v[238:239]
	v_pk_fma_f32 v[240:241], v[56:57], v[56:57], v[240:241]
	v_pk_fma_f32 v[240:241], v[58:59], v[58:59], v[240:241]
	v_cvt_pk_bf16_f32 v60, v60, v61
	v_cvt_pk_bf16_f32 v61, v62, v63
	v_cvt_pk_bf16_f32 v62, v56, v57
	v_cvt_pk_bf16_f32 v63, v58, v59
	global_store_dwordx4 v228, v[60:63], s[12:13]
	v_lshlrev_b32_e32 v232, 16, v196
	v_and_b32_e32 v233, 0xffff0000, v196
	v_lshlrev_b32_e32 v234, 16, v197
	v_and_b32_e32 v235, 0xffff0000, v197
	v_pk_add_f32 v[52:53], v[52:53], v[232:233]
	v_pk_add_f32 v[54:55], v[54:55], v[234:235]
	v_pk_fma_f32 v[240:241], v[52:53], v[52:53], v[240:241]
	v_pk_fma_f32 v[240:241], v[54:55], v[54:55], v[240:241]
	v_lshlrev_b32_e32 v236, 16, v198
	v_and_b32_e32 v237, 0xffff0000, v198
	v_lshlrev_b32_e32 v238, 16, v199
	v_and_b32_e32 v239, 0xffff0000, v199
	v_pk_add_f32 v[48:49], v[48:49], v[236:237]
	v_pk_add_f32 v[50:51], v[50:51], v[238:239]
	v_pk_fma_f32 v[240:241], v[48:49], v[48:49], v[240:241]
	v_pk_fma_f32 v[240:241], v[50:51], v[50:51], v[240:241]
	v_cvt_pk_bf16_f32 v52, v52, v53
	v_cvt_pk_bf16_f32 v53, v54, v55
	v_cvt_pk_bf16_f32 v54, v48, v49
	v_cvt_pk_bf16_f32 v55, v50, v51
	global_store_dwordx4 v228, v[52:55], s[12:13] offset:256
	v_add_f32_e32 v248, v240, v241
	v_lshlrev_b32_e32 v232, 16, v200
	v_and_b32_e32 v233, 0xffff0000, v200
	v_lshlrev_b32_e32 v234, 16, v201
	v_and_b32_e32 v235, 0xffff0000, v201
	v_pk_add_f32 v[44:45], v[44:45], v[232:233]
	v_pk_add_f32 v[46:47], v[46:47], v[234:235]
	v_pk_mul_f32 v[242:243], v[44:45], v[44:45]
	v_pk_fma_f32 v[242:243], v[46:47], v[46:47], v[242:243]
	v_lshlrev_b32_e32 v236, 16, v202
	v_and_b32_e32 v237, 0xffff0000, v202
	v_lshlrev_b32_e32 v238, 16, v203
	v_and_b32_e32 v239, 0xffff0000, v203
	v_pk_add_f32 v[40:41], v[40:41], v[236:237]
	v_pk_add_f32 v[42:43], v[42:43], v[238:239]
	v_pk_fma_f32 v[242:243], v[40:41], v[40:41], v[242:243]
	v_pk_fma_f32 v[242:243], v[42:43], v[42:43], v[242:243]
	v_cvt_pk_bf16_f32 v44, v44, v45
	v_cvt_pk_bf16_f32 v45, v46, v47
	v_cvt_pk_bf16_f32 v46, v40, v41
	v_cvt_pk_bf16_f32 v47, v42, v43
	global_store_dwordx4 v229, v[44:47], s[12:13]
	v_lshlrev_b32_e32 v232, 16, v204
	v_and_b32_e32 v233, 0xffff0000, v204
	v_lshlrev_b32_e32 v234, 16, v205
	v_and_b32_e32 v235, 0xffff0000, v205
	v_pk_add_f32 v[36:37], v[36:37], v[232:233]
	v_pk_add_f32 v[38:39], v[38:39], v[234:235]
	v_pk_fma_f32 v[242:243], v[36:37], v[36:37], v[242:243]
	v_pk_fma_f32 v[242:243], v[38:39], v[38:39], v[242:243]
	v_lshlrev_b32_e32 v236, 16, v206
	v_and_b32_e32 v237, 0xffff0000, v206
	v_lshlrev_b32_e32 v238, 16, v207
	v_and_b32_e32 v239, 0xffff0000, v207
	v_pk_add_f32 v[32:33], v[32:33], v[236:237]
	v_pk_add_f32 v[34:35], v[34:35], v[238:239]
	v_pk_fma_f32 v[242:243], v[32:33], v[32:33], v[242:243]
	v_pk_fma_f32 v[242:243], v[34:35], v[34:35], v[242:243]
	v_cvt_pk_bf16_f32 v36, v36, v37
	v_cvt_pk_bf16_f32 v37, v38, v39
	v_cvt_pk_bf16_f32 v38, v32, v33
	v_cvt_pk_bf16_f32 v39, v34, v35
	global_store_dwordx4 v229, v[36:39], s[12:13] offset:256
	v_add_f32_e32 v249, v242, v243
	v_lshlrev_b32_e32 v232, 16, v208
	v_and_b32_e32 v233, 0xffff0000, v208
	v_lshlrev_b32_e32 v234, 16, v209
	v_and_b32_e32 v235, 0xffff0000, v209
	v_pk_add_f32 v[28:29], v[28:29], v[232:233]
	v_pk_add_f32 v[30:31], v[30:31], v[234:235]
	v_pk_mul_f32 v[244:245], v[28:29], v[28:29]
	v_pk_fma_f32 v[244:245], v[30:31], v[30:31], v[244:245]
	v_lshlrev_b32_e32 v236, 16, v210
	v_and_b32_e32 v237, 0xffff0000, v210
	v_lshlrev_b32_e32 v238, 16, v211
	v_and_b32_e32 v239, 0xffff0000, v211
	v_pk_add_f32 v[24:25], v[24:25], v[236:237]
	v_pk_add_f32 v[26:27], v[26:27], v[238:239]
	v_pk_fma_f32 v[244:245], v[24:25], v[24:25], v[244:245]
	v_pk_fma_f32 v[244:245], v[26:27], v[26:27], v[244:245]
	v_cvt_pk_bf16_f32 v28, v28, v29
	v_cvt_pk_bf16_f32 v29, v30, v31
	v_cvt_pk_bf16_f32 v30, v24, v25
	v_cvt_pk_bf16_f32 v31, v26, v27
	global_store_dwordx4 v230, v[28:31], s[12:13]
	v_lshlrev_b32_e32 v232, 16, v212
	v_and_b32_e32 v233, 0xffff0000, v212
	v_lshlrev_b32_e32 v234, 16, v213
	v_and_b32_e32 v235, 0xffff0000, v213
	v_pk_add_f32 v[20:21], v[20:21], v[232:233]
	v_pk_add_f32 v[22:23], v[22:23], v[234:235]
	v_pk_fma_f32 v[244:245], v[20:21], v[20:21], v[244:245]
	v_pk_fma_f32 v[244:245], v[22:23], v[22:23], v[244:245]
	v_lshlrev_b32_e32 v236, 16, v214
	v_and_b32_e32 v237, 0xffff0000, v214
	v_lshlrev_b32_e32 v238, 16, v215
	v_and_b32_e32 v239, 0xffff0000, v215
	v_pk_add_f32 v[16:17], v[16:17], v[236:237]
	v_pk_add_f32 v[18:19], v[18:19], v[238:239]
	v_pk_fma_f32 v[244:245], v[16:17], v[16:17], v[244:245]
	v_pk_fma_f32 v[244:245], v[18:19], v[18:19], v[244:245]
	v_cvt_pk_bf16_f32 v20, v20, v21
	v_cvt_pk_bf16_f32 v21, v22, v23
	v_cvt_pk_bf16_f32 v22, v16, v17
	v_cvt_pk_bf16_f32 v23, v18, v19
	global_store_dwordx4 v230, v[20:23], s[12:13] offset:256
	v_add_f32_e32 v250, v244, v245
	v_lshlrev_b32_e32 v232, 16, v216
	v_and_b32_e32 v233, 0xffff0000, v216
	v_lshlrev_b32_e32 v234, 16, v217
	v_and_b32_e32 v235, 0xffff0000, v217
	v_pk_add_f32 v[12:13], v[12:13], v[232:233]
	v_pk_add_f32 v[14:15], v[14:15], v[234:235]
	v_pk_mul_f32 v[246:247], v[12:13], v[12:13]
	v_pk_fma_f32 v[246:247], v[14:15], v[14:15], v[246:247]
	v_lshlrev_b32_e32 v236, 16, v218
	v_and_b32_e32 v237, 0xffff0000, v218
	v_lshlrev_b32_e32 v238, 16, v219
	v_and_b32_e32 v239, 0xffff0000, v219
	v_pk_add_f32 v[8:9], v[8:9], v[236:237]
	v_pk_add_f32 v[10:11], v[10:11], v[238:239]
	v_pk_fma_f32 v[246:247], v[8:9], v[8:9], v[246:247]
	v_pk_fma_f32 v[246:247], v[10:11], v[10:11], v[246:247]
	v_cvt_pk_bf16_f32 v12, v12, v13
	v_cvt_pk_bf16_f32 v13, v14, v15
	v_cvt_pk_bf16_f32 v14, v8, v9
	v_cvt_pk_bf16_f32 v15, v10, v11
	global_store_dwordx4 v231, v[12:15], s[12:13]
	v_lshlrev_b32_e32 v232, 16, v220
	v_and_b32_e32 v233, 0xffff0000, v220
	v_lshlrev_b32_e32 v234, 16, v221
	v_and_b32_e32 v235, 0xffff0000, v221
	v_pk_add_f32 v[4:5], v[4:5], v[232:233]
	v_pk_add_f32 v[6:7], v[6:7], v[234:235]
	v_pk_fma_f32 v[246:247], v[4:5], v[4:5], v[246:247]
	v_pk_fma_f32 v[246:247], v[6:7], v[6:7], v[246:247]
	v_lshlrev_b32_e32 v236, 16, v222
	v_and_b32_e32 v237, 0xffff0000, v222
	v_lshlrev_b32_e32 v238, 16, v223
	v_and_b32_e32 v239, 0xffff0000, v223
	v_pk_add_f32 v[0:1], v[0:1], v[236:237]
	v_pk_add_f32 v[2:3], v[2:3], v[238:239]
	v_pk_fma_f32 v[246:247], v[0:1], v[0:1], v[246:247]
	v_pk_fma_f32 v[246:247], v[2:3], v[2:3], v[246:247]
	v_cvt_pk_bf16_f32 v4, v4, v5
	v_cvt_pk_bf16_f32 v5, v6, v7
	v_cvt_pk_bf16_f32 v6, v0, v1
	v_cvt_pk_bf16_f32 v7, v2, v3
	global_store_dwordx4 v231, v[4:7], s[12:13] offset:256
	v_add_f32_e32 v251, v246, v247
	s_nop 1
	v_permlane32_swap_b32_e32 v248, v249
	v_permlane32_swap_b32_e32 v250, v251
	v_add_f32_e32 v248, v248, v249
	v_add_f32_e32 v250, v250, v251
	s_nop 1
	v_permlane16_swap_b32_e32 v248, v250
	v_add_f32_e32 v248, v248, v250
	global_atomic_add_f32 v144, v248, s[14:15] offset:512
	s_and_b64 vcc, exec, s[4:5]
	s_mov_b64 s[4:5], -1
	s_cbranch_vccnz .LBB0_1693
	s_andn2_b64 vcc, exec, s[10:11]
	s_cbranch_vccnz .LBB0_1692
	s_barrier
	s_branch .LBB0_1692
